# mixer_out phase rewritten by hand: transposed MFMA product, gates and outputs accessed directly in global memory without LDS staging or barriers; O_local producers swapped to match
# baseline (speedup 1.0000x reference)
; __device__ __forceinline__ bf16_t f2bf(float f) { return (bf16_t)(pk2(f, 0.f) & 0xffffu); }
; __device__ __forceinline__ float fexp(float x) { return __expf(x); }
; #define LBAR() do { asm volatile("s_waitcnt lgkmcnt(0)" ::: "memory"); __builtin_amdgcn_s_barrier(); asm volatile("" ::: "memory"); } while (0)
; __device__ __forceinline__ void hgrn_unit(const Ctx& X, LAS unsigned char* hl, int b, int c, int h, int tid_h, int w4, int lane, int layer) {
;     ...
;         for (int ct = 0; ct < 4; ++ct)
; #pragma unroll
;             for (int j = 0; j < 4; ++j) { const int ii = 16 * I + 4 * q + j, col = 16 * ct + r;
;                 QT[ii * LT + col] = f2bf((ct <= I && ii >= col) ? acc[ct][j] : 0.f); }
;     }
;     LBAR();
;     {
; #pragma unroll
;         for (int e = 0; e < 16; ++e) { VT[(ds + e) * LT + i] = f2bf(vv[e]); KDT[(ds + e) * LT + i] = f2bf(kk[e] * fexp(G63[e] - Gi[e])); }
.LBB0_317:
	v_ashrrev_i32_e32 v96, 4, v130
	v_lshl_add_u32 v98, v96, 2, s39
	v_cmp_ge_i32_e32 vcc, v98, v91
	v_lshlrev_b32_e32 v99, 1, v91
	v_mul_lo_u32 v100, v98, s44
	v_cndmask_b32_e32 v18, 0, v18, vcc
	s_waitcnt lgkmcnt(0)
	v_cvt_pk_bf16_f32 v18, v18, v157
	v_add3_u32 v74, v74, v99, v100
	ds_write_b16 v74, v18
	v_or_b32_e32 v18, 1, v98
	v_cmp_ge_i32_e32 vcc, v18, v91
	v_or_b32_e32 v99, 16, v91
	v_readlane_b32 s6, v252, 48
	v_cndmask_b32_e32 v19, 0, v19, vcc
	v_cvt_pk_bf16_f32 v19, v19, v157
	ds_write_b16 v74, v19 offset:144
	v_or_b32_e32 v19, 2, v98
	v_cmp_ge_i32_e32 vcc, v19, v91
	v_readlane_b32 s7, v252, 49
	v_or_b32_e32 v22, 48, v91
	v_cndmask_b32_e32 v20, 0, v20, vcc
	v_cvt_pk_bf16_f32 v20, v20, v157
	ds_write_b16 v74, v20 offset:288
	v_or_b32_e32 v20, 3, v98
	v_cmp_ge_i32_e32 vcc, v20, v91
	v_and_b32_e32 v97, 0xffff0000, v6
	v_lshlrev_b32_e32 v6, 16, v6
	v_cndmask_b32_e32 v21, 0, v21, vcc
	v_cmp_lt_i32_e32 vcc, v98, v99
	s_or_b64 s[4:5], s[40:41], vcc
	v_cndmask_b32_e64 v14, v14, 0, s[4:5]
	v_cmp_lt_i32_e32 vcc, v18, v99
	v_cvt_pk_bf16_f32 v21, v21, v157
	ds_write_b16 v74, v21 offset:432
	v_cvt_pk_bf16_f32 v14, v14, v157
	s_or_b64 s[4:5], s[40:41], vcc
	ds_write_b16 v74, v14 offset:32
	v_cndmask_b32_e64 v14, v15, 0, s[4:5]
	v_cmp_lt_i32_e32 vcc, v19, v99
	v_cvt_pk_bf16_f32 v14, v14, v157
	s_or_b64 s[4:5], s[40:41], vcc
	ds_write_b16 v74, v14 offset:176
	v_cndmask_b32_e64 v14, v16, 0, s[4:5]
	v_cmp_lt_i32_e32 vcc, v20, v99
	v_cvt_pk_bf16_f32 v14, v14, v157
	s_or_b64 s[4:5], s[40:41], vcc
	ds_write_b16 v74, v14 offset:320
	v_cndmask_b32_e64 v14, v17, 0, s[4:5]
	v_cvt_pk_bf16_f32 v14, v14, v157
	ds_write_b16 v74, v14 offset:464
	v_or_b32_e32 v14, 32, v91
	v_cmp_lt_i32_e32 vcc, v98, v14
	s_or_b64 s[4:5], s[6:7], vcc
	v_cndmask_b32_e64 v15, v30, 0, s[4:5]
	v_cmp_lt_i32_e32 vcc, v18, v14
	v_cvt_pk_bf16_f32 v15, v15, v157
	s_or_b64 s[4:5], s[6:7], vcc
	ds_write_b16 v74, v15 offset:64
	v_cndmask_b32_e64 v15, v31, 0, s[4:5]
	v_cmp_lt_i32_e32 vcc, v19, v14
	v_cvt_pk_bf16_f32 v15, v15, v157
	s_or_b64 s[4:5], s[6:7], vcc
	v_cmp_lt_i32_e32 vcc, v20, v14
	ds_write_b16 v74, v15 offset:208
	v_cndmask_b32_e64 v15, v32, 0, s[4:5]
	s_or_b64 s[4:5], s[6:7], vcc
	v_readlane_b32 s6, v252, 52
	v_cndmask_b32_e64 v14, v33, 0, s[4:5]
	v_cmp_lt_i32_e32 vcc, v98, v22
	v_readlane_b32 s7, v252, 53
	v_cvt_pk_bf16_f32 v15, v15, v157
	ds_write_b16 v74, v15 offset:352
	v_cvt_pk_bf16_f32 v14, v14, v157
	s_or_b64 s[4:5], s[6:7], vcc
	ds_write_b16 v74, v14 offset:496
	v_cndmask_b32_e64 v14, v34, 0, s[4:5]
	v_cmp_lt_i32_e32 vcc, v18, v22
	v_cvt_pk_bf16_f32 v14, v14, v157
	s_or_b64 s[4:5], s[6:7], vcc
	ds_write_b16 v74, v14 offset:96
	v_cndmask_b32_e64 v14, v35, 0, s[4:5]
	v_cmp_lt_i32_e32 vcc, v19, v22
	v_cvt_pk_bf16_f32 v14, v14, v157
	s_or_b64 s[4:5], s[6:7], vcc
	ds_write_b16 v74, v14 offset:240
	v_cndmask_b32_e64 v14, v36, 0, s[4:5]
	v_cmp_lt_i32_e32 vcc, v20, v22
	v_cvt_pk_bf16_f32 v14, v14, v157
	s_or_b64 s[4:5], s[6:7], vcc
	v_sub_f32_e32 v15, v40, v38
	ds_write_b16 v74, v14 offset:384
	v_cndmask_b32_e64 v14, v37, 0, s[4:5]
	v_mul_f32_e32 v15, 0x3fb8aa3b, v15
	v_cvt_pk_bf16_f32 v14, v14, v157
	v_exp_f32_e32 v15, v15
	ds_write_b16 v74, v14 offset:528
	v_mul_u32_u24_e32 v14, 0x48, v73
	v_add_lshl_u32 v14, v14, v72, 1
	s_waitcnt lgkmcnt(0)
	s_barrier
	v_cvt_pk_bf16_f32 v6, v6, v157
	v_add_u32_e32 v16, v71, v14
	ds_write_b16 v16, v6
	v_mul_f32_e32 v6, v90, v15
	v_sub_f32_e32 v15, v41, v39
	v_mul_f32_e32 v15, 0x3fb8aa3b, v15
	v_exp_f32_e32 v15, v15
	v_cvt_pk_bf16_f32 v6, v6, v157
	v_add_u32_e32 v14, v70, v14
	ds_write_b16 v14, v6
	v_cvt_pk_bf16_f32 v6, v97, v157
	ds_write_b16 v16, v6 offset:144
	v_mul_f32_e32 v6, v89, v15
	v_sub_f32_e32 v15, v44, v42
	v_mul_f32_e32 v15, 0x3fb8aa3b, v15
	v_and_b32_e32 v29, 0xffff0000, v7
	v_lshlrev_b32_e32 v7, 16, v7
	v_cvt_pk_bf16_f32 v6, v6, v157
	v_exp_f32_e32 v15, v15
	ds_write_b16 v14, v6 offset:144
	v_cvt_pk_bf16_f32 v6, v7, v157
	v_sub_f32_e32 v7, v45, v43
	v_mul_f32_e32 v7, 0x3fb8aa3b, v7
	v_exp_f32_e32 v7, v7
	ds_write_b16 v16, v6 offset:288
	v_mul_f32_e32 v6, v88, v15
	v_cvt_pk_bf16_f32 v6, v6, v157
	ds_write_b16 v14, v6 offset:288
	v_cvt_pk_bf16_f32 v6, v29, v157
	ds_write_b16 v16, v6 offset:432
	v_mul_f32_e32 v6, v87, v7
	v_sub_f32_e32 v7, v48, v46
	v_mul_f32_e32 v7, 0x3fb8aa3b, v7
	v_exp_f32_e32 v7, v7
	v_cvt_pk_bf16_f32 v6, v6, v157
	v_and_b32_e32 v28, 0xffff0000, v8
	v_lshlrev_b32_e32 v8, 16, v8
	ds_write_b16 v14, v6 offset:432
	v_cvt_pk_bf16_f32 v6, v8, v157
	ds_write_b16 v16, v6 offset:576
	v_mul_f32_e32 v6, v86, v7
	v_sub_f32_e32 v7, v49, v47
	v_mul_f32_e32 v7, 0x3fb8aa3b, v7
	v_exp_f32_e32 v7, v7
	v_cvt_pk_bf16_f32 v6, v6, v157
	ds_write_b16 v14, v6 offset:576
	v_cvt_pk_bf16_f32 v6, v28, v157
	ds_write_b16 v16, v6 offset:720
	v_mul_f32_e32 v6, v85, v7
	v_sub_f32_e32 v7, v52, v50
	v_mul_f32_e32 v7, 0x3fb8aa3b, v7
	v_exp_f32_e32 v7, v7
	v_cvt_pk_bf16_f32 v6, v6, v157
	v_and_b32_e32 v27, 0xffff0000, v9
	v_lshlrev_b32_e32 v9, 16, v9
	ds_write_b16 v14, v6 offset:720
	v_cvt_pk_bf16_f32 v6, v9, v157
	ds_write_b16 v16, v6 offset:864
	v_mul_f32_e32 v6, v84, v7
	v_sub_f32_e32 v7, v53, v51
	v_mul_f32_e32 v7, 0x3fb8aa3b, v7
	v_exp_f32_e32 v7, v7
	v_cvt_pk_bf16_f32 v6, v6, v157
	ds_write_b16 v14, v6 offset:864
	v_cvt_pk_bf16_f32 v6, v27, v157
	ds_write_b16 v16, v6 offset:1008
	v_mul_f32_e32 v6, v83, v7
	v_sub_f32_e32 v7, v56, v54
	v_mul_f32_e32 v7, 0x3fb8aa3b, v7
	v_exp_f32_e32 v7, v7
	v_cvt_pk_bf16_f32 v6, v6, v157
	s_waitcnt vmcnt(2)
; __device__ __forceinline__ bf16_t f2bf(float f) { return (bf16_t)(pk2(f, 0.f) & 0xffffu); }
; __device__ __forceinline__ float fexp(float x) { return __expf(x); }
; #define LBAR() do { asm volatile("s_waitcnt lgkmcnt(0)" ::: "memory"); __builtin_amdgcn_s_barrier(); asm volatile("" ::: "memory"); } while (0)
; __device__ __forceinline__ void hgrn_unit(const Ctx& X, LAS unsigned char* hl, int b, int c, int h, int tid_h, int w4, int lane, int layer) {
;     ...
;         for (int e = 0; e < 16; ++e) { VT[(ds + e) * LT + i] = f2bf(vv[e]); KDT[(ds + e) * LT + i] = f2bf(kk[e] * fexp(G63[e] - Gi[e])); }
;     }
;     LBAR();
; #pragma unroll
;     for (int ct = 0; ct < 4; ++ct) acc[ct] = mma16(QT, 16 * w4, VT, 16 * ct, (f32x4){0.f, 0.f, 0.f, 0.f}, r, q);
;     store_oloc(WSP(bf16_t, WS_OLOC), uid, w4, lane, acc);
; #pragma unroll
;     for (int ct = 0; ct < 4; ++ct) acc[ct] = mma16(KDT, 16 * w4, VT, 16 * ct, (f32x4){0.f, 0.f, 0.f, 0.f}, r, q);
;     store_bc(WSP(bf16_t, WS_BCS), uid, w4, r, q, acc);
	v_and_b32_e32 v26, 0xffff0000, v10
	v_lshlrev_b32_e32 v10, 16, v10
	ds_write_b16 v14, v6 offset:1008
	v_cvt_pk_bf16_f32 v6, v10, v157
	ds_write_b16 v16, v6 offset:1152
	v_mul_f32_e32 v6, v82, v7
	v_sub_f32_e32 v7, v57, v55
	v_mul_f32_e32 v7, 0x3fb8aa3b, v7
	v_exp_f32_e32 v7, v7
	v_cvt_pk_bf16_f32 v6, v6, v157
	ds_write_b16 v14, v6 offset:1152
	v_cvt_pk_bf16_f32 v6, v26, v157
	ds_write_b16 v16, v6 offset:1296
	v_mul_f32_e32 v6, v81, v7
	v_sub_f32_e32 v7, v60, v58
	v_mul_f32_e32 v7, 0x3fb8aa3b, v7
	v_exp_f32_e32 v7, v7
	v_cvt_pk_bf16_f32 v6, v6, v157
	v_and_b32_e32 v25, 0xffff0000, v11
	v_lshlrev_b32_e32 v11, 16, v11
	ds_write_b16 v14, v6 offset:1296
	v_cvt_pk_bf16_f32 v6, v11, v157
	ds_write_b16 v16, v6 offset:1440
	v_mul_f32_e32 v6, v80, v7
	v_sub_f32_e32 v7, v61, v59
	v_mul_f32_e32 v7, 0x3fb8aa3b, v7
	v_exp_f32_e32 v7, v7
	v_cvt_pk_bf16_f32 v6, v6, v157
	ds_write_b16 v14, v6 offset:1440
	v_cvt_pk_bf16_f32 v6, v25, v157
	ds_write_b16 v16, v6 offset:1584
	v_mul_f32_e32 v6, v79, v7
	v_sub_f32_e32 v7, v64, v62
	v_mul_f32_e32 v7, 0x3fb8aa3b, v7
	v_exp_f32_e32 v7, v7
	v_cvt_pk_bf16_f32 v6, v6, v157
	v_and_b32_e32 v24, 0xffff0000, v12
	v_lshlrev_b32_e32 v12, 16, v12
	ds_write_b16 v14, v6 offset:1584
	v_cvt_pk_bf16_f32 v6, v12, v157
	ds_write_b16 v16, v6 offset:1728
	v_mul_f32_e32 v6, v78, v7
	v_sub_f32_e32 v7, v65, v63
	v_mul_f32_e32 v7, 0x3fb8aa3b, v7
	v_exp_f32_e32 v7, v7
	v_cvt_pk_bf16_f32 v6, v6, v157
	ds_write_b16 v14, v6 offset:1728
	v_cvt_pk_bf16_f32 v6, v24, v157
	ds_write_b16 v16, v6 offset:1872
	v_mul_f32_e32 v6, v77, v7
	v_sub_f32_e32 v7, v68, v66
	v_mul_f32_e32 v7, 0x3fb8aa3b, v7
	v_exp_f32_e32 v7, v7
	v_cvt_pk_bf16_f32 v6, v6, v157
	v_and_b32_e32 v23, 0xffff0000, v13
	v_lshlrev_b32_e32 v13, 16, v13
	ds_write_b16 v14, v6 offset:1872
	v_cvt_pk_bf16_f32 v6, v13, v157
	ds_write_b16 v16, v6 offset:2016
	v_mul_f32_e32 v6, v76, v7
	v_sub_f32_e32 v7, v69, v67
	v_mul_f32_e32 v7, 0x3fb8aa3b, v7
	v_exp_f32_e32 v7, v7
	v_cvt_pk_bf16_f32 v6, v6, v157
	ds_write_b16 v14, v6 offset:2016
	v_cvt_pk_bf16_f32 v6, v23, v157
	ds_write_b16 v16, v6 offset:2160
	v_mul_f32_e32 v6, v75, v7
	v_cvt_pk_bf16_f32 v6, v6, v157
	ds_write_b16 v14, v6 offset:2160
	s_waitcnt lgkmcnt(0)
	s_barrier
	ds_read_b128 v[6:9], v94
	ds_read_b128 v[10:13], v94 offset:64
	v_add_u32_e32 v22, v71, v92
	v_add_u32_e32 v44, v22, v95
	ds_read_b128 v[14:17], v44
	ds_read_b128 v[18:21], v44 offset:64
	s_waitcnt lgkmcnt(1)
	v_mfma_f32_16x16x32_bf16 v[14:17], v[14:17], v[6:9], 0
	v_mad_u32_u24 v34, v99, s44, v22
	s_add_u32 s4, s79, s0
	v_lshlrev_b32_e32 v42, 4, v130
	s_waitcnt lgkmcnt(0)
	v_mfma_f32_16x16x32_bf16 v[14:17], v[18:21], v[10:13], v[14:17]
	ds_read_b128 v[18:21], v34
	ds_read_b128 v[22:25], v34 offset:64
	s_addc_u32 s5, s80, s1
	v_ashrrev_i32_e32 v43, 31, v42
	s_waitcnt lgkmcnt(1)
	v_mfma_f32_16x16x32_bf16 v[18:21], v[18:21], v[6:9], 0
	s_add_u32 s0, s74, s0
	s_addc_u32 s1, s75, s1
	s_waitcnt lgkmcnt(0)
	v_mfma_f32_16x16x32_bf16 v[18:21], v[22:25], v[10:13], v[18:21]
	ds_read_b128 v[22:25], v34 offset:2304
	ds_read_b128 v[26:29], v34 offset:2368
	s_waitcnt lgkmcnt(1)
	v_mfma_f32_16x16x32_bf16 v[22:25], v[22:25], v[6:9], 0
	s_waitcnt lgkmcnt(0)
	v_mfma_f32_16x16x32_bf16 v[22:25], v[26:29], v[10:13], v[22:25]
	ds_read_b128 v[26:29], v44 offset:6912
	ds_read_b128 v[30:33], v44 offset:6976
	s_waitcnt lgkmcnt(1)
	v_mfma_f32_16x16x32_bf16 v[6:9], v[26:29], v[6:9], 0
	v_mul_u32_u24_e32 v26, 0x90, v93
	s_waitcnt lgkmcnt(0)
	v_mfma_f32_16x16x32_bf16 v[6:9], v[30:33], v[10:13], v[6:9]
	v_cvt_pk_bf16_f32 v10, v14, v15
	v_cvt_pk_bf16_f32 v11, v16, v17
	v_cvt_pk_bf16_f32 v12, v18, v19
	v_add3_u32 v18, v70, v26, v92
	v_cvt_pk_bf16_f32 v13, v20, v21
	v_cvt_pk_bf16_f32 v14, v22, v23
	v_cvt_pk_bf16_f32 v15, v24, v25
	v_cvt_pk_bf16_f32 v16, v6, v7
	v_cvt_pk_bf16_f32 v17, v8, v9
	s_nop 6
	ds_read_b128 v[6:9], v18
	ds_read_b128 v[18:21], v18 offset:64
	ds_read_b128 v[22:25], v44
	ds_read_b128 v[26:29], v44 offset:64
	s_waitcnt lgkmcnt(1)
	v_mfma_f32_16x16x32_bf16 v[22:25], v[6:9], v[22:25], 0
	s_waitcnt lgkmcnt(0)
	v_mfma_f32_16x16x32_bf16 v[22:25], v[18:21], v[26:29], v[22:25]
	ds_read_b128 v[26:29], v34
	ds_read_b128 v[30:33], v34 offset:64
	s_waitcnt lgkmcnt(1)
	v_mfma_f32_16x16x32_bf16 v[26:29], v[6:9], v[26:29], 0
	s_waitcnt lgkmcnt(0)
	v_mfma_f32_16x16x32_bf16 v[26:29], v[18:21], v[30:33], v[26:29]
	ds_read_b128 v[30:33], v34 offset:2304
	ds_read_b128 v[34:37], v34 offset:2368
	ds_read_b128 v[38:41], v44 offset:6912
	s_waitcnt lgkmcnt(2)
	v_mfma_f32_16x16x32_bf16 v[30:33], v[6:9], v[30:33], 0
	s_waitcnt lgkmcnt(1)
	v_mfma_f32_16x16x32_bf16 v[30:33], v[18:21], v[34:37], v[30:33]
	ds_read_b128 v[34:37], v44 offset:6976
	s_waitcnt lgkmcnt(1)
	v_mfma_f32_16x16x32_bf16 v[6:9], v[6:9], v[38:41], 0
	v_lshl_add_u64 v[38:39], v[42:43], 1, s[4:5]
	global_store_dwordx4 v[38:39], v[10:13], off nt
	global_store_dwordx4 v[38:39], v[14:17], off offset:16 nt
	s_nop 0
	v_lshl_or_b32 v12, v91, 2, s81
	v_lshl_add_u32 v12, v96, 6, v12
	v_ashrrev_i32_e32 v13, 31, v12
	v_cvt_pk_bf16_f32 v10, v22, v23
	v_cvt_pk_bf16_f32 v11, v24, v25
	v_lshl_add_u64 v[14:15], v[12:13], 1, s[0:1]
	global_store_dwordx2 v[14:15], v[10:11], off
	v_cvt_pk_bf16_f32 v10, v26, v27
	v_cvt_pk_bf16_f32 v11, v28, v29
	global_store_dwordx2 v[14:15], v[10:11], off offset:2048
	v_add_u32_e32 v14, 0x800, v12
	v_ashrrev_i32_e32 v15, 31, v14
	s_waitcnt lgkmcnt(0)
	v_mfma_f32_16x16x32_bf16 v[6:9], v[18:21], v[34:37], v[6:9]
	v_lshl_add_u64 v[14:15], v[14:15], 1, s[0:1]
	v_cvt_pk_bf16_f32 v10, v30, v31
	v_cvt_pk_bf16_f32 v11, v32, v33
	global_store_dwordx2 v[14:15], v[10:11], off
	v_cvt_pk_bf16_f32 v6, v6, v7
	v_cvt_pk_bf16_f32 v7, v8, v9
	s_nop 5
	v_add_u32_e32 v8, 0xc00, v12
	v_ashrrev_i32_e32 v9, 31, v8
	v_lshl_add_u64 v[8:9], v[8:9], 1, s[0:1]
	global_store_dwordx2 v[8:9], v[6:7], off
	s_waitcnt lgkmcnt(0)
	s_barrier
	s_mov_b64 s[0:1], 0

; __device__ __forceinline__ float bf2f(bf16_t b) { return __uint_as_float((unsigned)b << 16); }
; __device__ __forceinline__ bf16_t f2bf(float f) { return (bf16_t)(pk2(f, 0.f) & 0xffffu); }
; __device__ __forceinline__ float fexp(float x) { return __expf(x); }
; __device__ __forceinline__ void gdn_unit(const Ctx& X, LAS unsigned char* hl, int b, int c, int h, int tid_h, int w4, int lane, int layer) {
;     ...
;         f32x4 acc[4];
;         const float eG63 = fexp(Gs[63]);
; #pragma unroll
;         for (int ct = 0; ct < 4; ++ct) acc[ct] = mma16(P, 16 * w4, WT, 16 * ct, (f32x4){0.f, 0.f, 0.f, 0.f}, r, q);
;         bf16_t* qe = WSP(bf16_t, WS_QEFF) + (size_t)uid * 4096;
; #pragma unroll
;         for (int ct = 0; ct < 4; ++ct)
; #pragma unroll
;             for (int j = 0; j < 4; ++j) { const int ii = 16 * w4 + 4 * q + j, col = 16 * ct + r;
;                 qe[ii * 64 + col] = f2bf(bf2f(Q[ii * LT + col]) * fexp(Gs[ii]) - acc[ct][j]); }
.LBB0_619:
	s_waitcnt lgkmcnt(0)
	s_barrier
	ds_read_b32 v6, v185 offset:252
	v_add3_u32 v28, v184, v78, v69
	v_add3_u32 v27, v183, v69, v82
	s_lshl_b32 s0, s22, 9
	s_lshl_b32 s1, s23, 7
	s_waitcnt lgkmcnt(0)
	v_mul_f32_e32 v26, 0x3fb8aa3b, v6
	ds_read_b128 v[6:9], v28
	ds_read_b128 v[22:25], v28 offset:64
	ds_read_b128 v[10:13], v27
	ds_read_b128 v[14:17], v27 offset:64
	s_waitcnt lgkmcnt(1)
	v_mfma_f32_16x16x32_bf16 v[10:13], v[6:9], v[10:13], 0
	s_add_i32 s1, s1, s0
	s_or_b32 s0, s1, s21
	s_ashr_i32 s1, s0, 31
	s_waitcnt lgkmcnt(0)
	v_mfma_f32_16x16x32_bf16 v[18:21], v[22:25], v[14:17], v[10:13]
	ds_read_b128 v[14:17], v27 offset:2368
	s_lshl_b64 s[0:1], s[0:1], 13
	v_lshlrev_b32_e32 v34, 6, v73
	ds_read_b128 v[10:13], v27 offset:2304
	s_waitcnt lgkmcnt(0)
	v_mfma_f32_16x16x32_bf16 v[10:13], v[6:9], v[10:13], 0
	ds_read_b128 v[30:33], v27 offset:4672
	s_add_u32 s4, s89, s0
	s_addc_u32 s5, s78, s1
	v_mfma_f32_16x16x32_bf16 v[14:17], v[22:25], v[14:17], v[10:13]
	v_lshlrev_b32_e32 v35, 6, v74
	v_lshlrev_b32_e32 v36, 6, v75
	v_lshlrev_b32_e32 v37, 6, v76
	s_nop 0
	ds_read_b128 v[10:13], v27 offset:4608
	s_waitcnt lgkmcnt(0)
	v_mfma_f32_16x16x32_bf16 v[10:13], v[6:9], v[10:13], 0
	v_exp_f32_e32 v26, v26
	v_readlane_b32 s6, v253, 0
	v_cmp_eq_u32_e32 vcc, v73, v106
	v_mfma_f32_16x16x32_bf16 v[10:13], v[22:25], v[30:33], v[10:13]
	ds_read_b128 v[30:33], v27 offset:6912
	s_waitcnt lgkmcnt(0)
	v_mfma_f32_16x16x32_bf16 v[6:9], v[6:9], v[30:33], 0
	ds_read_b128 v[30:33], v27 offset:6976
	s_waitcnt lgkmcnt(0)
	v_mfma_f32_16x16x32_bf16 v[6:9], v[22:25], v[30:33], v[6:9]
	v_mul_lo_u32 v22, v73, s44
	v_lshlrev_b32_e32 v23, 1, v106
	v_add3_u32 v29, v182, v23, v22
	ds_read_b32 v23, v83
	ds_read_u16 v22, v29
	v_or_b32_e32 v30, v36, v106
	v_ashrrev_i32_e32 v31, 31, v30
	v_or_b32_e32 v32, v37, v106
	s_waitcnt lgkmcnt(1)
	v_mul_f32_e32 v23, 0x3fb8aa3b, v23
	v_exp_f32_e32 v23, v23
	s_waitcnt lgkmcnt(0)
	v_lshlrev_b32_e32 v22, 16, v22
	v_ashrrev_i32_e32 v33, 31, v32
	v_fma_f32 v18, v23, v22, -v18
	v_or_b32_e32 v22, v34, v106
	v_ashrrev_i32_e32 v23, 31, v22
	v_cvt_pk_bf16_f32 v18, v18, v157
	v_lshl_add_u64 v[24:25], v[22:23], 1, s[4:5]
	ds_read_b32 v23, v83 offset:4
	global_store_short v[24:25], v18, off
	ds_read_u16 v18, v29 offset:144
	v_or_b32_e32 v24, v35, v106
	v_ashrrev_i32_e32 v25, 31, v24
	s_waitcnt lgkmcnt(1)
	v_mul_f32_e32 v23, 0x3fb8aa3b, v23
	v_exp_f32_e32 v23, v23
	s_waitcnt lgkmcnt(0)
	v_lshlrev_b32_e32 v18, 16, v18
	v_fma_f32 v18, v23, v18, -v19
	v_cvt_pk_bf16_f32 v23, v18, v157
	v_lshl_add_u64 v[18:19], v[24:25], 1, s[4:5]
	global_store_short v[18:19], v23, off
	ds_read_b32 v19, v83 offset:8
	ds_read_u16 v18, v29 offset:288
	v_ashrrev_i32_e32 v23, 31, v34
	v_ashrrev_i32_e32 v25, 31, v35
	s_waitcnt lgkmcnt(1)
	v_mul_f32_e32 v19, 0x3fb8aa3b, v19
	v_exp_f32_e32 v19, v19
	s_waitcnt lgkmcnt(0)
	v_lshlrev_b32_e32 v18, 16, v18
	v_fma_f32 v18, v19, v18, -v20
	v_cvt_pk_bf16_f32 v20, v18, v157
	v_lshl_add_u64 v[18:19], v[30:31], 1, s[4:5]
	global_store_short v[18:19], v20, off
	ds_read_b32 v19, v83 offset:12
	ds_read_u16 v18, v29 offset:432
	v_ashrrev_i32_e32 v31, 31, v36
	s_waitcnt lgkmcnt(1)
	v_mul_f32_e32 v19, 0x3fb8aa3b, v19
	v_exp_f32_e32 v19, v19
	s_waitcnt lgkmcnt(0)
	v_lshlrev_b32_e32 v18, 16, v18
	v_fma_f32 v18, v19, v18, -v21
	v_cvt_pk_bf16_f32 v20, v18, v157
	v_lshl_add_u64 v[18:19], v[32:33], 1, s[4:5]
	global_store_short v[18:19], v20, off
	ds_read_b32 v19, v83
	ds_read_u16 v18, v29 offset:32
	v_ashrrev_i32_e32 v33, 31, v37
	s_waitcnt lgkmcnt(1)
	v_mul_f32_e32 v19, 0x3fb8aa3b, v19
	v_exp_f32_e32 v19, v19
	s_waitcnt lgkmcnt(0)
	v_lshlrev_b32_e32 v18, 16, v18
	v_fma_f32 v14, v19, v18, -v14
	v_cvt_pk_bf16_f32 v14, v14, v157
	ds_read_b32 v20, v83 offset:4
	v_lshl_add_u64 v[18:19], v[22:23], 1, s[4:5]
	global_store_short v[18:19], v14, off offset:32
	ds_read_u16 v14, v29 offset:176
	s_waitcnt lgkmcnt(1)
	v_mul_f32_e32 v20, 0x3fb8aa3b, v20
	v_exp_f32_e32 v20, v20
	s_waitcnt lgkmcnt(0)
	v_lshlrev_b32_e32 v14, 16, v14
	v_fma_f32 v14, v20, v14, -v15
	v_cvt_pk_bf16_f32 v20, v14, v157
	ds_read_b32 v21, v83 offset:8
	v_lshl_add_u64 v[14:15], v[24:25], 1, s[4:5]
	global_store_short v[14:15], v20, off offset:32
	ds_read_u16 v20, v29 offset:320
	s_waitcnt lgkmcnt(1)
	v_mul_f32_e32 v21, 0x3fb8aa3b, v21
	v_exp_f32_e32 v21, v21
	s_waitcnt lgkmcnt(0)
	v_lshlrev_b32_e32 v20, 16, v20
	v_fma_f32 v16, v21, v20, -v16
	v_cvt_pk_bf16_f32 v16, v16, v157
	ds_read_b32 v22, v83 offset:12
	v_lshl_add_u64 v[20:21], v[30:31], 1, s[4:5]
	global_store_short v[20:21], v16, off offset:32
	ds_read_u16 v16, v29 offset:464
	s_waitcnt lgkmcnt(1)
	v_mul_f32_e32 v22, 0x3fb8aa3b, v22
	v_exp_f32_e32 v22, v22
	s_waitcnt lgkmcnt(0)
	v_lshlrev_b32_e32 v16, 16, v16
	v_fma_f32 v16, v22, v16, -v17
	v_cvt_pk_bf16_f32 v22, v16, v157
	ds_read_b32 v23, v83
	v_lshl_add_u64 v[16:17], v[32:33], 1, s[4:5]
	global_store_short v[16:17], v22, off offset:32
	ds_read_u16 v22, v29 offset:64
	v_add3_u32 v32, v181, v69, v82
	s_waitcnt lgkmcnt(1)
	v_mul_f32_e32 v23, 0x3fb8aa3b, v23
	v_exp_f32_e32 v23, v23
	s_add_u32 s4, s79, s0
	s_waitcnt lgkmcnt(0)
	v_lshlrev_b32_e32 v22, 16, v22
	s_addc_u32 s5, s80, s1
	v_fma_f32 v10, v23, v22, -v10
	v_cvt_pk_bf16_f32 v10, v10, v157
	ds_read_b32 v22, v83 offset:4
	global_store_short v[18:19], v10, off offset:64
	ds_read_u16 v10, v29 offset:208
	v_add3_u32 v33, v131, v78, v69
	s_waitcnt lgkmcnt(1)
	v_mul_f32_e32 v22, 0x3fb8aa3b, v22
	v_exp_f32_e32 v22, v22
	s_waitcnt lgkmcnt(0)
	v_lshlrev_b32_e32 v10, 16, v10
	v_fma_f32 v10, v22, v10, -v11
	v_cvt_pk_bf16_f32 v10, v10, v157
	ds_read_b32 v11, v83 offset:8
	global_store_short v[14:15], v10, off offset:64
	ds_read_u16 v10, v29 offset:352
	s_waitcnt lgkmcnt(1)
; __device__ __forceinline__ float bf2f(bf16_t b) { return __uint_as_float((unsigned)b << 16); }
; __device__ __forceinline__ bf16_t f2bf(float f) { return (bf16_t)(pk2(f, 0.f) & 0xffffu); }
; __device__ __forceinline__ float fexp(float x) { return __expf(x); }
; __device__ __forceinline__ void gdn_unit(const Ctx& X, LAS unsigned char* hl, int b, int c, int h, int tid_h, int w4, int lane, int layer) {
;     ...
;                 qe[ii * 64 + col] = f2bf(bf2f(Q[ii * LT + col]) * fexp(Gs[ii]) - acc[ct][j]); }
; #pragma unroll
;         for (int ct = 0; ct < 4; ++ct) acc[ct] = mma16(P, 16 * w4, UT, 16 * ct, (f32x4){0.f, 0.f, 0.f, 0.f}, r, q);
;         store_oloc(WSP(bf16_t, WS_OLOC), uid, w4, lane, acc);
	v_mul_f32_e32 v11, 0x3fb8aa3b, v11
	v_exp_f32_e32 v11, v11
	s_waitcnt lgkmcnt(0)
	v_lshlrev_b32_e32 v10, 16, v10
	v_fma_f32 v10, v11, v10, -v12
	v_cvt_pk_bf16_f32 v10, v10, v157
	ds_read_b32 v11, v83 offset:12
	global_store_short v[20:21], v10, off offset:64
	ds_read_u16 v10, v29 offset:496
	s_waitcnt lgkmcnt(1)
	v_mul_f32_e32 v11, 0x3fb8aa3b, v11
	v_exp_f32_e32 v11, v11
	s_waitcnt lgkmcnt(0)
	v_lshlrev_b32_e32 v10, 16, v10
	v_fma_f32 v10, v11, v10, -v13
	v_cvt_pk_bf16_f32 v10, v10, v157
	ds_read_b32 v11, v83
	global_store_short v[16:17], v10, off offset:64
	ds_read_u16 v10, v29 offset:96
	s_waitcnt lgkmcnt(1)
	v_mul_f32_e32 v11, 0x3fb8aa3b, v11
	v_exp_f32_e32 v11, v11
	s_waitcnt lgkmcnt(0)
	v_lshlrev_b32_e32 v10, 16, v10
	v_fma_f32 v6, v11, v10, -v6
	v_cvt_pk_bf16_f32 v6, v6, v157
	ds_read_b32 v10, v83 offset:4
	global_store_short v[18:19], v6, off offset:96
	ds_read_u16 v6, v29 offset:240
	s_waitcnt lgkmcnt(1)
	v_mul_f32_e32 v10, 0x3fb8aa3b, v10
	v_exp_f32_e32 v10, v10
	s_waitcnt lgkmcnt(0)
	v_lshlrev_b32_e32 v6, 16, v6
	v_fma_f32 v6, v10, v6, -v7
	v_cvt_pk_bf16_f32 v6, v6, v157
	ds_read_b32 v7, v83 offset:8
	global_store_short v[14:15], v6, off offset:96
	ds_read_u16 v6, v29 offset:384
	s_waitcnt lgkmcnt(1)
	v_mul_f32_e32 v7, 0x3fb8aa3b, v7
	v_exp_f32_e32 v7, v7
	s_waitcnt lgkmcnt(0)
	v_lshlrev_b32_e32 v6, 16, v6
	v_fma_f32 v6, v7, v6, -v8
	v_cvt_pk_bf16_f32 v6, v6, v157
	ds_read_b32 v7, v83 offset:12
	global_store_short v[20:21], v6, off offset:96
	ds_read_u16 v6, v29 offset:528
	s_waitcnt lgkmcnt(1)
	v_mul_f32_e32 v7, 0x3fb8aa3b, v7
	v_exp_f32_e32 v7, v7
	s_waitcnt lgkmcnt(0)
	v_lshlrev_b32_e32 v6, 16, v6
	v_fma_f32 v6, v7, v6, -v9
	v_cvt_pk_bf16_f32 v6, v6, v157
	global_store_short v[16:17], v6, off offset:96
	ds_read_b128 v[6:9], v28
	ds_read_b128 v[10:13], v28 offset:64
	ds_read_b128 v[14:17], v32
	ds_read_b128 v[18:21], v32 offset:64
	s_waitcnt lgkmcnt(1)
	v_mfma_f32_16x16x32_bf16 v[14:17], v[14:17], v[6:9], 0
	ds_read_b128 v[22:25], v32 offset:2368
	ds_read_b128 v[28:31], v32 offset:4672
	s_waitcnt lgkmcnt(2)
	v_mfma_f32_16x16x32_bf16 v[14:17], v[18:21], v[10:13], v[14:17]
	ds_read_b128 v[18:21], v32 offset:2304
	s_waitcnt lgkmcnt(0)
	v_mfma_f32_16x16x32_bf16 v[18:21], v[18:21], v[6:9], 0
	v_mfma_f32_16x16x32_bf16 v[18:21], v[22:25], v[10:13], v[18:21]
	ds_read_b128 v[22:25], v32 offset:4608
	s_waitcnt lgkmcnt(0)
	v_mfma_f32_16x16x32_bf16 v[22:25], v[22:25], v[6:9], 0
	v_mfma_f32_16x16x32_bf16 v[22:25], v[28:31], v[10:13], v[22:25]
	ds_read_b128 v[28:31], v32 offset:6912
	s_waitcnt lgkmcnt(0)
	v_mfma_f32_16x16x32_bf16 v[6:9], v[28:31], v[6:9], 0
	ds_read_b128 v[28:31], v32 offset:6976
	s_waitcnt lgkmcnt(0)
	v_mfma_f32_16x16x32_bf16 v[6:9], v[28:31], v[10:13], v[6:9]
	v_lshlrev_b32_e32 v10, 4, v130
	v_ashrrev_i32_e32 v11, 31, v10
	v_lshl_add_u64 v[28:29], v[10:11], 1, s[4:5]
	v_cvt_pk_bf16_f32 v10, v14, v15
	v_cvt_pk_bf16_f32 v11, v16, v17
	v_cvt_pk_bf16_f32 v12, v18, v19
	v_cvt_pk_bf16_f32 v13, v20, v21
	v_cvt_pk_bf16_f32 v14, v22, v23
	v_cvt_pk_bf16_f32 v15, v24, v25
	v_cvt_pk_bf16_f32 v16, v6, v7
	v_cvt_pk_bf16_f32 v17, v8, v9
	global_store_dwordx4 v[28:29], v[10:13], off nt
	global_store_dwordx4 v[28:29], v[14:17], off offset:16 nt
	s_nop 2
	ds_read_b128 v[6:9], v33
	ds_read_b128 v[10:13], v33 offset:64
	ds_read_b128 v[14:17], v27
	ds_read_b128 v[18:21], v27 offset:64
	ds_read_b128 v[22:25], v27 offset:2368
	s_waitcnt lgkmcnt(2)
	v_mfma_f32_16x16x32_bf16 v[14:17], v[6:9], v[14:17], 0
	ds_read_b128 v[28:31], v27 offset:4672
	v_readlane_b32 s4, v253, 3
	s_add_u32 s4, s4, s0
	s_waitcnt lgkmcnt(2)
	v_mfma_f32_16x16x32_bf16 v[14:17], v[10:13], v[18:21], v[14:17]
	ds_read_b128 v[18:21], v27 offset:2304
	v_readlane_b32 s5, v253, 4
	s_addc_u32 s5, s5, s1
	s_waitcnt lgkmcnt(0)
	v_mfma_f32_16x16x32_bf16 v[18:21], v[6:9], v[18:21], 0
	s_add_u32 s4, s4, 0xff000000
	s_addc_u32 s5, s5, -1
	s_add_u32 s0, s74, s0
	v_mfma_f32_16x16x32_bf16 v[18:21], v[10:13], v[22:25], v[18:21]
	ds_read_b128 v[22:25], v27 offset:4608
	s_addc_u32 s1, s75, s1
	s_waitcnt lgkmcnt(0)
	v_mfma_f32_16x16x32_bf16 v[22:25], v[6:9], v[22:25], 0
	v_mfma_f32_16x16x32_bf16 v[22:25], v[10:13], v[28:31], v[22:25]
	ds_read_b128 v[28:31], v27 offset:6912
	s_waitcnt lgkmcnt(0)
	v_mfma_f32_16x16x32_bf16 v[6:9], v[6:9], v[28:31], 0
	ds_read_b128 v[28:31], v27 offset:6976
	v_and_b32_e32 v27, 3, v130
	s_waitcnt lgkmcnt(0)
; __device__ __forceinline__ bf16_t f2bf(float f) { return (bf16_t)(pk2(f, 0.f) & 0xffffu); }
; __device__ __forceinline__ void gdn_unit(const Ctx& X, LAS unsigned char* hl, int b, int c, int h, int tid_h, int w4, int lane, int layer) {
;     ...
;         for (int ct = 0; ct < 4; ++ct) acc[ct] = mma16(KDT, 16 * w4, WT, 16 * ct, (f32x4){0.f, 0.f, 0.f, 0.f}, r, q);
;         bf16_t* mm = WSP(bf16_t, WS_MM) + (size_t)(uid - 2048) * 4096;
; #pragma unroll
;         for (int ct = 0; ct < 4; ++ct)
; #pragma unroll
;             for (int j = 0; j < 4; ++j) { const int ii = 16 * w4 + 4 * q + j, col = 16 * ct + r;
;                 mm[((w4 * 2 + (ct >> 1)) * 64 + (r >> 2) * 16 + 4 * q + j) * 8 + (ct & 1) * 4 + (r & 3)] = f2bf((ii == col ? eG63 : 0.f) - acc[ct][j]); }
; #pragma unroll
;         for (int ct = 0; ct < 4; ++ct) acc[ct] = mma16(KDT, 16 * w4, UT, 16 * ct, (f32x4){0.f, 0.f, 0.f, 0.f}, r, q);
;         store_bc(WSP(bf16_t, WS_BCS), uid, w4, r, q, acc);
	v_mfma_f32_16x16x32_bf16 v[6:9], v[10:13], v[28:31], v[6:9]
	v_and_b32_e32 v10, 48, v68
	v_add_u32_e32 v11, s6, v77
	v_add_lshl_u32 v28, v11, v10, 3
	v_cndmask_b32_e32 v12, 0, v26, vcc
	v_or_b32_e32 v10, v28, v27
	v_sub_f32_e32 v12, v12, v14
	v_ashrrev_i32_e32 v11, 31, v10
	v_cmp_eq_u32_e32 vcc, v74, v106
	v_cvt_pk_bf16_f32 v14, v12, v157
	v_lshl_add_u64 v[12:13], v[10:11], 1, s[4:5]
	global_store_short v[12:13], v14, off
	v_cndmask_b32_e32 v11, 0, v26, vcc
	v_sub_f32_e32 v11, v11, v15
	v_cvt_pk_bf16_f32 v14, v11, v157
	v_ashrrev_i32_e32 v11, 31, v28
	v_lshl_add_u64 v[12:13], v[10:11], 1, s[4:5]
	v_cmp_eq_u32_e32 vcc, v75, v106
	global_store_short v[12:13], v14, off offset:16
	v_or_b32_e32 v10, 4, v10
	v_cndmask_b32_e32 v14, 0, v26, vcc
	v_sub_f32_e32 v14, v14, v16
	v_cvt_pk_bf16_f32 v14, v14, v157
	v_cmp_eq_u32_e32 vcc, v76, v106
	global_store_short v[12:13], v14, off offset:32
	v_lshl_add_u64 v[10:11], v[10:11], 1, s[4:5]
	v_cndmask_b32_e32 v14, 0, v26, vcc
	v_sub_f32_e32 v14, v14, v17
	v_cvt_pk_bf16_f32 v14, v14, v157
	v_cmp_eq_u32_e32 vcc, v73, v79
	global_store_short v[12:13], v14, off offset:48
	s_nop 0
	v_cndmask_b32_e32 v14, 0, v26, vcc
	v_sub_f32_e32 v14, v14, v18
	v_cmp_eq_u32_e32 vcc, v74, v79
	v_cvt_pk_bf16_f32 v14, v14, v157
	global_store_short v[12:13], v14, off offset:8
	s_nop 0
	v_cndmask_b32_e32 v12, 0, v26, vcc
	v_sub_f32_e32 v12, v12, v19
	v_cvt_pk_bf16_f32 v12, v12, v157
	v_cmp_eq_u32_e32 vcc, v75, v79
	global_store_short v[10:11], v12, off offset:16
	s_nop 0
	v_cndmask_b32_e32 v12, 0, v26, vcc
	v_sub_f32_e32 v12, v12, v20
	v_cvt_pk_bf16_f32 v12, v12, v157
	v_cmp_eq_u32_e32 vcc, v76, v79
	global_store_short v[10:11], v12, off offset:32
	v_add_u32_e32 v20, 0x200, v28
	v_cndmask_b32_e32 v12, 0, v26, vcc
	v_sub_f32_e32 v12, v12, v21
	v_cmp_eq_u32_e32 vcc, v73, v80
	v_cvt_pk_bf16_f32 v12, v12, v157
	global_store_short v[10:11], v12, off offset:48
	v_add_u32_e32 v21, 0x208, v28
	v_cndmask_b32_e32 v10, 0, v26, vcc
	v_sub_f32_e32 v10, v10, v22
	v_cvt_pk_bf16_f32 v14, v10, v157
	v_or_b32_e32 v10, v20, v27
	v_ashrrev_i32_e32 v11, 31, v10
	v_lshl_add_u64 v[12:13], v[10:11], 1, s[4:5]
	v_cmp_eq_u32_e32 vcc, v74, v80
	global_store_short v[12:13], v14, off
	v_or_b32_e32 v12, v21, v27
	v_cndmask_b32_e32 v11, 0, v26, vcc
	v_sub_f32_e32 v11, v11, v23
	v_ashrrev_i32_e32 v13, 31, v12
	v_cvt_pk_bf16_f32 v11, v11, v157
	v_lshl_add_u64 v[14:15], v[12:13], 1, s[4:5]
	v_cmp_eq_u32_e32 vcc, v75, v80
	v_add_u32_e32 v22, 0x210, v28
	global_store_short v[14:15], v11, off
	v_cndmask_b32_e32 v11, 0, v26, vcc
	v_or_b32_e32 v14, v22, v27
	v_sub_f32_e32 v11, v11, v24
	v_ashrrev_i32_e32 v15, 31, v14
	v_cvt_pk_bf16_f32 v11, v11, v157
	v_lshl_add_u64 v[16:17], v[14:15], 1, s[4:5]
	v_cmp_eq_u32_e32 vcc, v76, v80
	v_add_u32_e32 v23, 0x218, v28
	global_store_short v[16:17], v11, off
	v_cndmask_b32_e32 v11, 0, v26, vcc
	v_or_b32_e32 v16, v23, v27
	v_sub_f32_e32 v11, v11, v25
	v_ashrrev_i32_e32 v17, 31, v16
	v_cvt_pk_bf16_f32 v11, v11, v157
	v_lshl_add_u64 v[18:19], v[16:17], 1, s[4:5]
	v_cmp_eq_u32_e32 vcc, v73, v81
	global_store_short v[18:19], v11, off
	v_ashrrev_i32_e32 v13, 31, v21
	v_cndmask_b32_e32 v11, 0, v26, vcc
	v_sub_f32_e32 v6, v11, v6
	v_ashrrev_i32_e32 v11, 31, v20
	v_cvt_pk_bf16_f32 v6, v6, v157
	v_lshl_add_u64 v[10:11], v[10:11], 1, s[4:5]
	v_cmp_eq_u32_e32 vcc, v74, v81
	global_store_short v[10:11], v6, off offset:8
	v_ashrrev_i32_e32 v15, 31, v22
	v_cndmask_b32_e32 v6, 0, v26, vcc
	v_sub_f32_e32 v6, v6, v7
	v_cvt_pk_bf16_f32 v10, v6, v157
	v_lshl_add_u64 v[6:7], v[12:13], 1, s[4:5]
	v_cmp_eq_u32_e32 vcc, v75, v81
	global_store_short v[6:7], v10, off offset:8
	v_ashrrev_i32_e32 v17, 31, v23
	v_cndmask_b32_e32 v6, 0, v26, vcc
	v_sub_f32_e32 v6, v6, v8
	v_cvt_pk_bf16_f32 v8, v6, v157
	v_lshl_add_u64 v[6:7], v[14:15], 1, s[4:5]
	v_cmp_eq_u32_e32 vcc, v76, v81
	global_store_short v[6:7], v8, off offset:8
	s_nop 0
	v_cndmask_b32_e32 v6, 0, v26, vcc
	v_sub_f32_e32 v6, v6, v9
	v_cvt_pk_bf16_f32 v8, v6, v157
	v_lshl_add_u64 v[6:7], v[16:17], 1, s[4:5]
	global_store_short v[6:7], v8, off offset:8
	ds_read_b128 v[6:9], v33
	ds_read_b128 v[10:13], v33 offset:64
	ds_read_b128 v[14:17], v32
	ds_read_b128 v[18:21], v32 offset:64
	ds_read_b128 v[22:25], v32 offset:2368
	s_waitcnt lgkmcnt(2)
	v_mfma_f32_16x16x32_bf16 v[14:17], v[6:9], v[14:17], 0
	ds_read_b128 v[26:29], v32 offset:4672
	s_waitcnt lgkmcnt(2)
	v_mfma_f32_16x16x32_bf16 v[14:17], v[10:13], v[18:21], v[14:17]
	ds_read_b128 v[18:21], v32 offset:2304
	s_waitcnt lgkmcnt(0)
	v_mfma_f32_16x16x32_bf16 v[18:21], v[6:9], v[18:21], 0
	v_mfma_f32_16x16x32_bf16 v[18:21], v[10:13], v[22:25], v[18:21]
	ds_read_b128 v[22:25], v32 offset:4608
	s_waitcnt lgkmcnt(0)
	v_mfma_f32_16x16x32_bf16 v[22:25], v[6:9], v[22:25], 0
	v_mfma_f32_16x16x32_bf16 v[22:25], v[10:13], v[26:29], v[22:25]
	ds_read_b128 v[26:29], v32 offset:6912
	s_waitcnt lgkmcnt(0)
	v_mfma_f32_16x16x32_bf16 v[6:9], v[6:9], v[26:29], 0
	ds_read_b128 v[26:29], v32 offset:6976
	s_waitcnt lgkmcnt(0)
	v_mfma_f32_16x16x32_bf16 v[6:9], v[10:13], v[26:29], v[6:9]
	v_or_b32_e32 v12, s81, v68
	v_lshl_add_u32 v12, v72, 6, v12
	v_ashrrev_i32_e32 v13, 31, v12
	v_cvt_pk_bf16_f32 v10, v14, v15
	v_cvt_pk_bf16_f32 v11, v16, v17
	v_lshl_add_u64 v[14:15], v[12:13], 1, s[0:1]
	global_store_dwordx2 v[14:15], v[10:11], off
	v_cvt_pk_bf16_f32 v10, v18, v19
	v_cvt_pk_bf16_f32 v11, v20, v21
	global_store_dwordx2 v[14:15], v[10:11], off offset:2048
	v_add_u32_e32 v14, 0x800, v12
	v_ashrrev_i32_e32 v15, 31, v14
	v_lshl_add_u64 v[14:15], v[14:15], 1, s[0:1]
	v_cvt_pk_bf16_f32 v10, v22, v23
	v_cvt_pk_bf16_f32 v11, v24, v25
	global_store_dwordx2 v[14:15], v[10:11], off
	v_cvt_pk_bf16_f32 v6, v6, v7
	v_cvt_pk_bf16_f32 v7, v8, v9
	v_add_u32_e32 v8, 0xc00, v12
	v_ashrrev_i32_e32 v9, 31, v8
	v_lshl_add_u64 v[8:9], v[8:9], 1, s[0:1]
	global_store_dwordx2 v[8:9], v[6:7], off
	s_waitcnt lgkmcnt(0)
	s_barrier
	s_mov_b64 s[0:1], 0

; __device__ __forceinline__ bf16_t f2bf(float f) { return (bf16_t)(pk2(f, 0.f) & 0xffffu); }
; __device__ __forceinline__ float fexp(float x) { return __expf(x); }
; #define LBAR() do { asm volatile("s_waitcnt lgkmcnt(0)" ::: "memory"); __builtin_amdgcn_s_barrier(); asm volatile("" ::: "memory"); } while (0)
; __device__ __forceinline__ void ret_unit(const Ctx& X, LAS unsigned char* hl, int b, int c, int h, int tid_h, int w4, int lane) {
;     ...
;     f32x4 acc[4];
; #pragma unroll
;     for (int ct = 0; ct < 4; ++ct) acc[ct] = mma16(QR, 16 * w4, KR, 16 * ct, (f32x4){0.f, 0.f, 0.f, 0.f}, r, q);
; #pragma unroll
;     for (int ct = 0; ct < 4; ++ct)
; #pragma unroll
;         for (int j = 0; j < 4; ++j) { const int ii = 16 * w4 + 4 * q + j, col = 16 * ct + r;
;             P[ii * LT + col] = f2bf(ii >= col ? acc[ct][j] * fexp(lg * (float)(ii - col)) : 0.f); }
;     LBAR();
.LpfR_done:
	v_or_b32_e32 v6, s39, v32
	v_mul_u32_u24_e32 v19, 0x90, v6
	v_add3_u32 v10, v37, v19, v20
	v_mad_u32_u24 v14, v32, s44, v29
	ds_read_b128 v[6:9], v10
	ds_read_b128 v[38:41], v10 offset:64
	ds_read_b128 v[10:13], v14
	ds_read_b128 v[14:17], v14 offset:64
	s_waitcnt lgkmcnt(1)
	v_mfma_f32_16x16x32_bf16 v[10:13], v[6:9], v[10:13], 0
	v_ashrrev_i32_e32 v18, 4, v130
	v_or_b32_e32 v31, 16, v32
	v_or_b32_e32 v28, 32, v32
	s_waitcnt lgkmcnt(0)
	v_mfma_f32_16x16x32_bf16 v[42:45], v[38:41], v[14:17], v[10:13]
	s_add_u32 s4, s79, s0
	s_addc_u32 s5, s80, s1
	s_add_u32 s0, s74, s0
	v_mov_b32_e32 v10, 0x900
	v_mad_u32_u24 v21, v32, s44, v10
	v_add_u32_e32 v14, v29, v21
	ds_read_b128 v[10:13], v14
	ds_read_b128 v[14:17], v14 offset:64
	s_waitcnt lgkmcnt(1)
	v_mfma_f32_16x16x32_bf16 v[10:13], v[6:9], v[10:13], 0
	s_addc_u32 s1, s75, s1
	s_waitcnt lgkmcnt(0)
	v_mfma_f32_16x16x32_bf16 v[14:17], v[38:41], v[14:17], v[10:13]
	s_nop 4
	v_mov_b32_e32 v10, 0x1200
	v_mad_u32_u24 v22, v32, s44, v10
	v_add_u32_e32 v23, v29, v22
	ds_read_b128 v[10:13], v23
	ds_read_b128 v[24:27], v23 offset:64
	s_waitcnt lgkmcnt(1)
	v_mfma_f32_16x16x32_bf16 v[10:13], v[6:9], v[10:13], 0
	v_mov_b32_e32 v23, 0x1b00
	v_mad_u32_u24 v23, v32, s44, v23
	s_waitcnt lgkmcnt(0)
	v_mfma_f32_16x16x32_bf16 v[10:13], v[38:41], v[24:27], v[10:13]
	v_lshl_add_u32 v27, v18, 2, s39
	v_sub_u32_e32 v26, v27, v32
	v_cvt_f32_i32_e32 v26, v26
	v_add_u32_e32 v25, v29, v23
	ds_read_b128 v[46:49], v25
	v_cmp_ge_i32_e32 vcc, v27, v32
	v_mul_f32_e32 v26, v36, v26
	v_mul_f32_e32 v26, 0x3fb8aa3b, v26
	v_exp_f32_e32 v26, v26
	s_waitcnt lgkmcnt(0)
	v_mfma_f32_16x16x32_bf16 v[6:9], v[6:9], v[46:49], 0
	ds_read_b128 v[46:49], v25 offset:64
	v_lshlrev_b32_e32 v25, 1, v32
	v_mul_f32_e32 v26, v26, v42
	v_cndmask_b32_e32 v26, 0, v26, vcc
	v_mul_lo_u32 v29, v27, s44
	v_cvt_pk_bf16_f32 v26, v26, v157
	v_add3_u32 v25, v35, v25, v29
	v_or_b32_e32 v30, 1, v27
	ds_write_b16 v25, v26
	v_sub_u32_e32 v26, v30, v32
	v_cvt_f32_i32_e32 v26, v26
	v_cmp_ge_i32_e32 vcc, v30, v32
	v_or_b32_e32 v29, 2, v27
	v_or_b32_e32 v24, 48, v32
	v_mul_f32_e32 v26, v36, v26
	v_mul_f32_e32 v26, 0x3fb8aa3b, v26
	v_exp_f32_e32 v26, v26
	s_waitcnt lgkmcnt(1)
	v_mfma_f32_16x16x32_bf16 v[6:9], v[38:41], v[46:49], v[6:9]
	v_add_u32_e32 v38, v34, v20
	v_mad_u32_u24 v39, v32, s44, v38
	v_mul_f32_e32 v26, v26, v43
	v_cndmask_b32_e32 v26, 0, v26, vcc
	v_cvt_pk_bf16_f32 v26, v26, v157
	ds_write_b16 v25, v26 offset:144
	v_sub_u32_e32 v26, v29, v32
	v_cvt_f32_i32_e32 v26, v26
	v_cmp_ge_i32_e32 vcc, v29, v32
	v_add_u32_e32 v40, v38, v21
	v_add_u32_e32 v41, v38, v22
	v_mul_f32_e32 v26, v36, v26
	v_mul_f32_e32 v26, 0x3fb8aa3b, v26
	v_exp_f32_e32 v26, v26
	v_add_u32_e32 v38, v38, v23
	v_mul_f32_e32 v26, v26, v44
	v_cndmask_b32_e32 v26, 0, v26, vcc
	v_cvt_pk_bf16_f32 v26, v26, v157
	ds_write_b16 v25, v26 offset:288
	v_or_b32_e32 v26, 3, v27
	v_sub_u32_e32 v37, v26, v32
	v_cvt_f32_i32_e32 v37, v37
	v_cmp_ge_i32_e32 vcc, v26, v32
	v_mul_f32_e32 v37, v36, v37
	v_mul_f32_e32 v37, 0x3fb8aa3b, v37
	v_exp_f32_e32 v37, v37
	s_nop 0
	v_mul_f32_e32 v37, v37, v45
	v_cndmask_b32_e32 v37, 0, v37, vcc
	v_cvt_pk_bf16_f32 v37, v37, v157
	ds_write_b16 v25, v37 offset:432
	v_sub_u32_e32 v37, v27, v31
	v_cvt_f32_i32_e32 v37, v37
	v_cmp_ge_i32_e32 vcc, v27, v31
	v_mul_f32_e32 v37, v36, v37
	v_mul_f32_e32 v37, 0x3fb8aa3b, v37
	v_exp_f32_e32 v37, v37
	s_nop 0
	v_mul_f32_e32 v14, v37, v14
	v_cndmask_b32_e32 v14, 0, v14, vcc
	v_cvt_pk_bf16_f32 v14, v14, v157
	ds_write_b16 v25, v14 offset:32
	v_sub_u32_e32 v14, v30, v31
	v_cvt_f32_i32_e32 v14, v14
	v_cmp_ge_i32_e32 vcc, v30, v31
	v_mul_f32_e32 v14, v36, v14
	v_mul_f32_e32 v14, 0x3fb8aa3b, v14
	v_exp_f32_e32 v14, v14
	s_nop 0
	v_mul_f32_e32 v14, v14, v15
	v_cndmask_b32_e32 v14, 0, v14, vcc
	v_cvt_pk_bf16_f32 v14, v14, v157
	ds_write_b16 v25, v14 offset:176
	v_sub_u32_e32 v14, v29, v31
	v_cvt_f32_i32_e32 v14, v14
	v_cmp_ge_i32_e32 vcc, v29, v31
	v_mul_f32_e32 v14, v36, v14
	v_mul_f32_e32 v14, 0x3fb8aa3b, v14
	v_exp_f32_e32 v14, v14
	s_nop 0
	v_mul_f32_e32 v14, v14, v16
	v_cndmask_b32_e32 v14, 0, v14, vcc
	v_cvt_pk_bf16_f32 v14, v14, v157
	ds_write_b16 v25, v14 offset:320
	v_sub_u32_e32 v14, v26, v31
	v_cvt_f32_i32_e32 v14, v14
	v_cmp_ge_i32_e32 vcc, v26, v31
	v_mul_f32_e32 v14, v36, v14
	v_mul_f32_e32 v14, 0x3fb8aa3b, v14
	v_exp_f32_e32 v14, v14
	s_nop 0
	v_mul_f32_e32 v14, v14, v17
	v_cndmask_b32_e32 v14, 0, v14, vcc
	v_cvt_pk_bf16_f32 v14, v14, v157
	ds_write_b16 v25, v14 offset:464
	v_sub_u32_e32 v14, v27, v28
	v_cvt_f32_i32_e32 v14, v14
	v_cmp_ge_i32_e32 vcc, v27, v28
	v_mul_f32_e32 v14, v36, v14
	v_mul_f32_e32 v14, 0x3fb8aa3b, v14
	v_exp_f32_e32 v14, v14
	s_nop 0
	v_mul_f32_e32 v10, v14, v10
	v_cndmask_b32_e32 v10, 0, v10, vcc
	v_cvt_pk_bf16_f32 v10, v10, v157
	ds_write_b16 v25, v10 offset:64
	v_sub_u32_e32 v10, v30, v28
	v_cvt_f32_i32_e32 v10, v10
	v_cmp_ge_i32_e32 vcc, v30, v28
	v_mul_f32_e32 v10, v36, v10
	v_mul_f32_e32 v10, 0x3fb8aa3b, v10
	v_exp_f32_e32 v10, v10
	s_nop 0
	v_mul_f32_e32 v10, v10, v11
	v_cndmask_b32_e32 v10, 0, v10, vcc
	v_cvt_pk_bf16_f32 v10, v10, v157
	ds_write_b16 v25, v10 offset:208
	v_sub_u32_e32 v10, v29, v28
	v_cvt_f32_i32_e32 v10, v10
	v_cmp_ge_i32_e32 vcc, v29, v28
	v_mul_f32_e32 v10, v36, v10
	v_mul_f32_e32 v10, 0x3fb8aa3b, v10
	v_exp_f32_e32 v10, v10
	s_nop 0
	v_mul_f32_e32 v10, v10, v12
	v_cndmask_b32_e32 v10, 0, v10, vcc
	v_cvt_pk_bf16_f32 v10, v10, v157
	ds_write_b16 v25, v10 offset:352
	v_sub_u32_e32 v10, v26, v28
	v_cvt_f32_i32_e32 v10, v10
	v_cmp_ge_i32_e32 vcc, v26, v28
	v_mul_f32_e32 v10, v36, v10
	v_mul_f32_e32 v10, 0x3fb8aa3b, v10
	v_exp_f32_e32 v10, v10
	s_nop 0
	v_mul_f32_e32 v10, v10, v13
	v_cndmask_b32_e32 v10, 0, v10, vcc
	v_cvt_pk_bf16_f32 v10, v10, v157
	ds_write_b16 v25, v10 offset:496
	v_sub_u32_e32 v10, v27, v24
	v_cvt_f32_i32_e32 v10, v10
	v_cmp_ge_i32_e32 vcc, v27, v24
	v_mul_f32_e32 v10, v36, v10
	v_mul_f32_e32 v10, 0x3fb8aa3b, v10
	v_exp_f32_e32 v10, v10
	s_nop 0
	v_mul_f32_e32 v6, v10, v6
	v_cndmask_b32_e32 v6, 0, v6, vcc
	v_cvt_pk_bf16_f32 v6, v6, v157
	ds_write_b16 v25, v6 offset:96
	v_sub_u32_e32 v6, v30, v24
	v_cvt_f32_i32_e32 v6, v6
	v_cmp_ge_i32_e32 vcc, v30, v24
	v_add3_u32 v10, v35, v19, v20
	v_mul_f32_e32 v6, v36, v6
	v_mul_f32_e32 v6, 0x3fb8aa3b, v6
	v_exp_f32_e32 v6, v6
	s_nop 0
	v_mul_f32_e32 v6, v6, v7
	v_cndmask_b32_e32 v6, 0, v6, vcc
	v_cvt_pk_bf16_f32 v6, v6, v157
	ds_write_b16 v25, v6 offset:240
	v_sub_u32_e32 v6, v29, v24
	v_cvt_f32_i32_e32 v6, v6
	v_cmp_ge_i32_e32 vcc, v29, v24
	v_mul_f32_e32 v6, v36, v6
	v_mul_f32_e32 v6, 0x3fb8aa3b, v6
	v_exp_f32_e32 v6, v6
	s_nop 0
	v_mul_f32_e32 v6, v6, v8
	v_cndmask_b32_e32 v6, 0, v6, vcc
	v_cvt_pk_bf16_f32 v6, v6, v157
	ds_write_b16 v25, v6 offset:384
	v_sub_u32_e32 v6, v26, v24
	v_cvt_f32_i32_e32 v6, v6
	v_cmp_ge_i32_e32 vcc, v26, v24
	v_mul_f32_e32 v6, v36, v6
	v_mul_f32_e32 v6, 0x3fb8aa3b, v6
	v_exp_f32_e32 v6, v6
	s_nop 0
	v_mul_f32_e32 v6, v6, v9
	v_cndmask_b32_e32 v6, 0, v6, vcc
	v_cvt_pk_bf16_f32 v6, v6, v157
	ds_write_b16 v25, v6 offset:528
	s_waitcnt lgkmcnt(0)
	s_barrier
; #define LBAR() do { asm volatile("s_waitcnt lgkmcnt(0)" ::: "memory"); __builtin_amdgcn_s_barrier(); asm volatile("" ::: "memory"); } while (0)
; __device__ __forceinline__ void ret_unit(const Ctx& X, LAS unsigned char* hl, int b, int c, int h, int tid_h, int w4, int lane) {
;     ...
; #pragma unroll
;     for (int ct = 0; ct < 4; ++ct) acc[ct] = mma16(P, 16 * w4, VT, 16 * ct, (f32x4){0.f, 0.f, 0.f, 0.f}, r, q);
;     store_oloc(WSP(bf16_t, WS_OLOC), uid, w4, lane, acc);
; #pragma unroll
;     for (int ct = 0; ct < 4; ++ct) acc[ct] = mma16(KDT, 16 * w4, VT, 16 * ct, (f32x4){0.f, 0.f, 0.f, 0.f}, r, q);
;     store_bc(WSP(bf16_t, WS_BCS), uid, w4, r, q, acc);
;     LBAR();
	ds_read_b128 v[6:9], v10
	ds_read_b128 v[10:13], v10 offset:64
	ds_read_b128 v[14:17], v39
	ds_read_b128 v[24:27], v39 offset:64
	s_waitcnt lgkmcnt(1)
	v_mfma_f32_16x16x32_bf16 v[14:17], v[14:17], v[6:9], 0
	ds_read_b128 v[28:31], v40 offset:64
	ds_read_b128 v[34:37], v41 offset:64
	s_waitcnt lgkmcnt(2)
	v_mfma_f32_16x16x32_bf16 v[14:17], v[24:27], v[10:13], v[14:17]
	ds_read_b128 v[24:27], v40
	s_waitcnt lgkmcnt(0)
	v_mfma_f32_16x16x32_bf16 v[24:27], v[24:27], v[6:9], 0
	v_mfma_f32_16x16x32_bf16 v[24:27], v[28:31], v[10:13], v[24:27]
	ds_read_b128 v[28:31], v41
	s_waitcnt lgkmcnt(0)
	v_mfma_f32_16x16x32_bf16 v[28:31], v[28:31], v[6:9], 0
	v_mfma_f32_16x16x32_bf16 v[28:31], v[34:37], v[10:13], v[28:31]
	ds_read_b128 v[34:37], v38
	s_waitcnt lgkmcnt(0)
	v_mfma_f32_16x16x32_bf16 v[6:9], v[34:37], v[6:9], 0
	ds_read_b128 v[34:37], v38 offset:64
	s_waitcnt lgkmcnt(0)
	v_mfma_f32_16x16x32_bf16 v[6:9], v[34:37], v[10:13], v[6:9]
	v_lshlrev_b32_e32 v10, 4, v130
	v_ashrrev_i32_e32 v11, 31, v10
	v_lshl_add_u64 v[22:23], v[10:11], 1, s[4:5]
	v_cvt_pk_bf16_f32 v10, v14, v15
	v_cvt_pk_bf16_f32 v11, v16, v17
	v_cvt_pk_bf16_f32 v12, v24, v25
	v_cvt_pk_bf16_f32 v13, v26, v27
	v_cvt_pk_bf16_f32 v14, v28, v29
	v_cvt_pk_bf16_f32 v15, v30, v31
	v_cvt_pk_bf16_f32 v16, v6, v7
	v_cvt_pk_bf16_f32 v17, v8, v9
	global_store_dwordx4 v[22:23], v[10:13], off nt
	global_store_dwordx4 v[22:23], v[14:17], off offset:16 nt
	s_nop 0
	v_add3_u32 v10, v33, v19, v20
	s_nop 0
	ds_read_b128 v[6:9], v10
	ds_read_b128 v[10:13], v10 offset:64
	ds_read_b128 v[14:17], v39
	ds_read_b128 v[20:23], v39 offset:64
	ds_read_b128 v[24:27], v40 offset:64
	s_waitcnt lgkmcnt(2)
	v_mfma_f32_16x16x32_bf16 v[14:17], v[6:9], v[14:17], 0
	ds_read_b128 v[28:31], v41 offset:64
	s_waitcnt lgkmcnt(2)
	v_mfma_f32_16x16x32_bf16 v[14:17], v[10:13], v[20:23], v[14:17]
	ds_read_b128 v[20:23], v40
	s_waitcnt lgkmcnt(0)
	v_mfma_f32_16x16x32_bf16 v[20:23], v[6:9], v[20:23], 0
	v_mfma_f32_16x16x32_bf16 v[20:23], v[10:13], v[24:27], v[20:23]
	ds_read_b128 v[24:27], v41
	s_waitcnt lgkmcnt(0)
	v_mfma_f32_16x16x32_bf16 v[24:27], v[6:9], v[24:27], 0
	v_mfma_f32_16x16x32_bf16 v[24:27], v[10:13], v[28:31], v[24:27]
	ds_read_b128 v[28:31], v38
	s_waitcnt lgkmcnt(0)
	v_mfma_f32_16x16x32_bf16 v[6:9], v[6:9], v[28:31], 0
	ds_read_b128 v[28:31], v38 offset:64
	s_waitcnt lgkmcnt(0)
	v_mfma_f32_16x16x32_bf16 v[6:9], v[10:13], v[28:31], v[6:9]
	v_lshl_or_b32 v12, v32, 2, s81
	v_lshl_add_u32 v12, v18, 6, v12
	v_ashrrev_i32_e32 v13, 31, v12
	v_cvt_pk_bf16_f32 v10, v14, v15
	v_cvt_pk_bf16_f32 v11, v16, v17
	v_lshl_add_u64 v[14:15], v[12:13], 1, s[0:1]
	global_store_dwordx2 v[14:15], v[10:11], off
	v_cvt_pk_bf16_f32 v10, v20, v21
	v_cvt_pk_bf16_f32 v11, v22, v23
	global_store_dwordx2 v[14:15], v[10:11], off offset:2048
	v_add_u32_e32 v14, 0x800, v12
	v_ashrrev_i32_e32 v15, 31, v14
	v_lshl_add_u64 v[14:15], v[14:15], 1, s[0:1]
	v_cvt_pk_bf16_f32 v10, v24, v25
	v_cvt_pk_bf16_f32 v11, v26, v27
	global_store_dwordx2 v[14:15], v[10:11], off
	v_cvt_pk_bf16_f32 v6, v6, v7
	v_cvt_pk_bf16_f32 v7, v8, v9
	v_add_u32_e32 v8, 0xc00, v12
	v_ashrrev_i32_e32 v9, 31, v8
	v_lshl_add_u64 v[8:9], v[8:9], 1, s[0:1]
	global_store_dwordx2 v[8:9], v[6:7], off
	s_waitcnt lgkmcnt(0)
	s_barrier
	s_branch .LBB0_233

; #define LAS __attribute__((address_space(3)))
; __device__ __forceinline__ void mixer_out_phase(const Ctx& X, LAS unsigned char* lds, int layer, int tid, int wave, int lane) {
;     constexpr int GP = 264;
;     const bf16_t* proj = WSP(const bf16_t, WS_PROJ);
;     bf16_t* mix = WSP(bf16_t, WS_MIX);
;     for (int u = blockIdx.x; u < 1536; u += gridDim.x) {
;         asm volatile("" : "+v"(lane), "+v"(tid));
;         LAS bf16_t* GT = opq((LAS bf16_t*)lds);
;         const int r = lane & 15, q = lane >> 4, h = wave >> 1, half = wave & 1;
;         const int mixer = u >> 9, rem = u & 511, b = rem >> 7, c = rem & 127;
;         const int uid = unit_id(mixer, b, h, c);
;         const int goff = mixer == 0 ? C_RG : (mixer == 1 ? C_GG : C_HG), moff = mixer == 0 ? 0 : (mixer == 1 ? 512 : 768);
;         const size_t row0 = (size_t)b * T + c * 64;
;         u32x4 gv[4];
; #pragma unroll
;         for (int n = 0; n < 4; ++n) { const int idx = tid + 512 * n; gv[n] = *(const u32x4*)(proj + (row0 + (idx >> 5)) * LDP + goff + (idx & 31) * 8); }
;         const bf16_t* qe = WSP(const bf16_t, WS_QEFF) + (size_t)uid * 4096;
;         const bf16_t* st = WSP(const bf16_t, WS_BCS) + (size_t)uid * 4096;
;         bf16x8 a[2][2], bb[4][2]; u32x4 ov[2][2];
; #pragma unroll
;         for (int rt = 0; rt < 2; ++rt) { const int rt4 = 2 * half + rt;
; #pragma unroll
;             for (int ks = 0; ks < 2; ++ks) a[rt][ks] = *(const bf16x8*)(qe + (16 * rt4 + r) * 64 + ks * 32 + q * 8);
;             const u32x4* ol = (const u32x4*)(WSP(const bf16_t, WS_OLOC) + ((size_t)uid * 4 + rt4) * 1024 + lane * 16); ov[rt][0] = ol[0]; ov[rt][1] = ol[1]; }
; #pragma unroll
;         for (int ct = 0; ct < 4; ++ct)
; #pragma unroll
;             for (int ks = 0; ks < 2; ++ks) { const bf16_t* tb = st + (size_t)((ct * 4 + 2 * ks + (q >> 1)) * 64) * 4;
;                 const u32x2 lo = *(const u32x2*)(tb + ((2 * (q & 1)) * 16 + r) * 4), hi = *(const u32x2*)(tb + ((2 * (q & 1) + 1) * 16 + r) * 4);
;                 bb[ct][ks] = __builtin_bit_cast(bf16x8, (u32x4){lo.x, lo.y, hi.x, hi.y}); }
;         const float* nw = mixer == 0 ? X.in[3] + layer * 256 + h * 64 : (mixer == 1 ? X.in[11] + layer * 64 : X.in[13] + layer * 64);
;         float wv[4];
; #pragma unroll
;         for (int ct = 0; ct < 4; ++ct) wv[ct] = nw[16 * ct + r];
; #pragma unroll
.LBB0_886:
	s_or_b64 exec, exec, s[0:1]
	v_readlane_b32 s0, v253, 56
	v_readlane_b32 s1, v253, 57
	s_andn2_b64 vcc, exec, s[0:1]
	s_waitcnt lgkmcnt(0)
	s_barrier
	s_cbranch_vccnz .LBB0_890
	v_readfirstlane_b32 s0, v224
	v_and_b32_e32 v6, 15, v232
	v_lshrrev_b32_e32 v7, 4, v232
	s_lshr_b32 s0, s0, 6
	s_lshr_b32 s1, s0, 1
	s_and_b32 s11, s0, 1
	v_lshlrev_b32_e32 v8, 7, v6
	v_lshl_add_u32 v8, v7, 4, v8
	v_lshlrev_b32_e32 v9, 5, v232
	v_and_b32_e32 v10, 1, v7
	v_lshl_add_u32 v10, v10, 5, v6
	v_lshlrev_b32_e32 v10, 3, v10
	v_lshrrev_b32_e32 v11, 1, v7
	v_lshl_add_u32 v10, v11, 9, v10
	v_add_u32_e32 v11, 0x1000, v10
	v_mul_u32_u24_e32 v12, 0x1c00, v6
	v_lshl_add_u32 v12, v7, 3, v12
	v_lshlrev_b32_e32 v13, 11, v6
	v_lshl_add_u32 v13, v7, 3, v13
	v_lshlrev_b32_e32 v14, 4, v7
	v_xor_b32_e32 v15, 16, v232
	v_lshlrev_b32_e32 v15, 2, v15
	v_xor_b32_e32 v146, 32, v232
	v_lshlrev_b32_e32 v146, 2, v146
	s_mov_b32 s10, s2
.Lmo_loop:
	s_lshr_b32 s4, s10, 9
	s_and_b32 s7, s10, 0x1ff
	s_lshr_b32 s5, s7, 7
	s_and_b32 s6, s7, 0x7f
	s_lshl_b32 s7, s4, 2
	s_add_u32 s7, s7, s5
	s_lshl_b32 s7, s7, 2
	s_add_u32 s7, s7, s1
	s_lshl_b32 s7, s7, 7
	s_add_u32 s7, s7, s6
	s_lshl_b32 s7, s7, 13
	s_lshl_b32 s16, s11, 12
	s_add_u32 s100, s7, s16
	s_add_u32 s8, s100, 0x19600000
	s_add_u32 s8, s30, s8
	s_addc_u32 s9, s31, 0
	s_add_u32 s12, s100, 0x1c600000
	s_add_u32 s12, s30, s12
	s_addc_u32 s13, s31, 0
	s_add_u32 s14, s7, 0x3500000
	s_add_u32 s14, s30, s14
	s_addc_u32 s15, s31, 0
	s_lshl_b32 s7, s5, 13
	s_lshl_b32 s16, s6, 6
	s_add_u32 s7, s7, s16
	s_lshl_b32 s16, s11, 5
	s_add_u32 s7, s7, s16
	s_movk_i32 s100, 0x1200
	s_cmp_eq_u32 s4, 0
	s_cselect_b32 s100, 0x600, s100
	s_cselect_b32 s101, 0, 0x400
	s_cselect_b32 s19, 0x3c800000, 0
	s_cmp_eq_u32 s4, 2
	s_cselect_b32 s100, 0x1a00, s100
	s_cselect_b32 s101, 0x600, s101
	s_lshl_b32 s16, s1, 7
	s_add_u32 s100, s100, s16
	s_add_u32 s101, s101, s16
	s_mul_i32 s16, s7, 0x1c00
	s_add_u32 s16, s16, s100
	s_add_u32 s20, s76, s16
	s_addc_u32 s21, s77, 0
	s_add_u32 s22, s20, 0x1c000
	s_addc_u32 s23, s21, 0
	s_lshl_b32 s16, s7, 11
	s_add_u32 s16, s16, s101
	s_add_u32 s16, s16, 0x7500000
	s_add_u32 s44, s30, s16
	s_addc_u32 s45, s31, 0
	s_add_u32 s46, s44, 0x8000
	s_addc_u32 s47, s45, 0
	v_readlane_b32 s100, v254, 61
	v_readlane_b32 s48, v252, 6
	v_readlane_b32 s49, v252, 7
	v_readlane_b32 s50, v253, 44
	v_readlane_b32 s51, v253, 45
	v_readlane_b32 s52, v253, 48
	v_readlane_b32 s53, v253, 49
	s_lshl_b32 s101, s100, 10
	s_lshl_b32 s16, s1, 8
	s_add_u32 s101, s101, s16
	s_lshl_b32 s100, s100, 8
	s_cmp_eq_u32 s4, 1
	s_cselect_b32 s48, s50, s48
	s_cselect_b32 s49, s51, s49
	s_cselect_b32 s101, s100, s101
	s_cmp_eq_u32 s4, 2
	s_cselect_b32 s48, s52, s48
	s_cselect_b32 s49, s53, s49
	s_cselect_b32 s101, s100, s101
	s_add_u32 s48, s48, s101
	s_addc_u32 s49, s49, 0
	s_mov_b32 s16, 0x358637bd
	s_cmp_eq_u32 s4, 0
	s_cselect_b32 s16, 0x3727c5ac, s16
	v_mov_b32_e32 v147, s16
	global_load_dwordx4 v[16:19], v8, s[8:9]
	global_load_dwordx4 v[20:23], v8, s[8:9] offset:64
	global_load_dwordx4 v[24:27], v8, s[8:9] offset:2048
	global_load_dwordx4 v[28:31], v8, s[8:9] offset:2112
	global_load_dwordx2 v[32:33], v10, s[14:15]
	global_load_dwordx2 v[34:35], v10, s[14:15] offset:128
	global_load_dwordx2 v[36:37], v10, s[14:15] offset:1024
	global_load_dwordx2 v[38:39], v10, s[14:15] offset:1152
	global_load_dwordx2 v[40:41], v10, s[14:15] offset:2048
	global_load_dwordx2 v[42:43], v10, s[14:15] offset:2176
	global_load_dwordx2 v[44:45], v10, s[14:15] offset:3072
	global_load_dwordx2 v[46:47], v10, s[14:15] offset:3200
	global_load_dwordx2 v[48:49], v11, s[14:15]
	global_load_dwordx2 v[50:51], v11, s[14:15] offset:128
	global_load_dwordx2 v[52:53], v11, s[14:15] offset:1024
	global_load_dwordx2 v[54:55], v11, s[14:15] offset:1152
	global_load_dwordx2 v[56:57], v11, s[14:15] offset:2048
	global_load_dwordx2 v[58:59], v11, s[14:15] offset:2176
	global_load_dwordx2 v[60:61], v11, s[14:15] offset:3072
	global_load_dwordx2 v[62:63], v11, s[14:15] offset:3200
	global_load_dwordx4 v[64:67], v9, s[12:13]
	global_load_dwordx4 v[68:71], v9, s[12:13] offset:16
	global_load_dwordx4 v[72:75], v9, s[12:13] offset:2048
	global_load_dwordx4 v[76:79], v9, s[12:13] offset:2064
	global_load_dwordx4 v[96:99], v14, s[48:49]
	global_load_dwordx4 v[100:103], v14, s[48:49] offset:64
	global_load_dwordx4 v[104:107], v14, s[48:49] offset:128
	global_load_dwordx4 v[108:111], v14, s[48:49] offset:192
	global_load_dwordx2 v[80:81], v12, s[20:21]
	global_load_dwordx2 v[82:83], v12, s[20:21] offset:32
	global_load_dwordx2 v[84:85], v12, s[20:21] offset:64
	global_load_dwordx2 v[86:87], v12, s[20:21] offset:96
	global_load_dwordx2 v[88:89], v12, s[22:23]
	global_load_dwordx2 v[90:91], v12, s[22:23] offset:32
	global_load_dwordx2 v[92:93], v12, s[22:23] offset:64
	global_load_dwordx2 v[94:95], v12, s[22:23] offset:96
	s_waitcnt vmcnt(12)
; __device__ __forceinline__ float bf_lo(unsigned u) { return __uint_as_float(u << 16); }
; __device__ __forceinline__ float bf_hi(unsigned u) { return __uint_as_float(u & 0xffff0000u); }
; __device__ __forceinline__ void mixer_out_phase(const Ctx& X, LAS unsigned char* lds, int layer, int tid, int wave, int lane) {
;     ...
;         for (int rt = 0; rt < 2; ++rt) {
;             f32x4 acc[4];
;             acc[0] = (f32x4){bf_lo(ov[rt][0].x), bf_hi(ov[rt][0].x), bf_lo(ov[rt][0].y), bf_hi(ov[rt][0].y)}; acc[1] = (f32x4){bf_lo(ov[rt][0].z), bf_hi(ov[rt][0].z), bf_lo(ov[rt][0].w), bf_hi(ov[rt][0].w)};
;             acc[2] = (f32x4){bf_lo(ov[rt][1].x), bf_hi(ov[rt][1].x), bf_lo(ov[rt][1].y), bf_hi(ov[rt][1].y)}; acc[3] = (f32x4){bf_lo(ov[rt][1].z), bf_hi(ov[rt][1].z), bf_lo(ov[rt][1].w), bf_hi(ov[rt][1].w)};
; #pragma unroll
;             for (int ct = 0; ct < 4; ++ct)
; #pragma unroll
;                 for (int ks = 0; ks < 2; ++ks) acc[ct] = __builtin_amdgcn_mfma_f32_16x16x32_bf16(a[rt][ks], bb[ct][ks], acc[ct], 0, 0, 0);
; #pragma unroll
;             for (int j = 0; j < 4; ++j) {
;                 float sm = (acc[0][j] + acc[1][j]) + (acc[2][j] + acc[3][j]);
;                 sm += __shfl_xor(sm, 1); sm += __shfl_xor(sm, 2); sm += __shfl_xor(sm, 4); sm += __shfl_xor(sm, 8);
;                 const float mu = mixer == 0 ? sm * (1.f / 64.f) : 0.f;
;                 float d[4], s2 = 0.f;
; #pragma unroll
;                 for (int ct = 0; ct < 4; ++ct) { d[ct] = acc[ct][j] - mu; s2 += d[ct] * d[ct]; }
;                 s2 += __shfl_xor(s2, 1); s2 += __shfl_xor(s2, 2); s2 += __shfl_xor(s2, 4); s2 += __shfl_xor(s2, 8);
;                 const float rs = rsqrtf(s2 * (1.f / 64.f) + (mixer == 0 ? 1e-5f : 1e-6f));
	v_lshlrev_b32_e32 v114, 16, v64
	v_and_b32_e32 v115, 0xffff0000, v64
	v_lshlrev_b32_e32 v116, 16, v65
	v_and_b32_e32 v117, 0xffff0000, v65
	v_lshlrev_b32_e32 v118, 16, v66
	v_and_b32_e32 v119, 0xffff0000, v66
	v_lshlrev_b32_e32 v120, 16, v67
	v_and_b32_e32 v121, 0xffff0000, v67
	v_lshlrev_b32_e32 v122, 16, v68
	v_and_b32_e32 v123, 0xffff0000, v68
	v_lshlrev_b32_e32 v124, 16, v69
	v_and_b32_e32 v125, 0xffff0000, v69
	v_lshlrev_b32_e32 v126, 16, v70
	v_and_b32_e32 v127, 0xffff0000, v70
	v_lshlrev_b32_e32 v128, 16, v71
	v_and_b32_e32 v129, 0xffff0000, v71
	v_lshlrev_b32_e32 v130, 16, v72
	v_and_b32_e32 v131, 0xffff0000, v72
	v_lshlrev_b32_e32 v132, 16, v73
	v_and_b32_e32 v133, 0xffff0000, v73
	v_lshlrev_b32_e32 v134, 16, v74
	v_and_b32_e32 v135, 0xffff0000, v74
	v_lshlrev_b32_e32 v136, 16, v75
	v_and_b32_e32 v137, 0xffff0000, v75
	v_lshlrev_b32_e32 v138, 16, v76
	v_and_b32_e32 v139, 0xffff0000, v76
	v_lshlrev_b32_e32 v140, 16, v77
	v_and_b32_e32 v141, 0xffff0000, v77
	v_lshlrev_b32_e32 v142, 16, v78
	v_and_b32_e32 v143, 0xffff0000, v78
	v_lshlrev_b32_e32 v144, 16, v79
	v_and_b32_e32 v145, 0xffff0000, v79
	s_nop 1
	v_mfma_f32_16x16x32_bf16 v[114:117], v[32:35], v[16:19], v[114:117]
	v_mfma_f32_16x16x32_bf16 v[118:121], v[40:43], v[16:19], v[118:121]
	v_mfma_f32_16x16x32_bf16 v[122:125], v[48:51], v[16:19], v[122:125]
	v_mfma_f32_16x16x32_bf16 v[126:129], v[56:59], v[16:19], v[126:129]
	v_mfma_f32_16x16x32_bf16 v[130:133], v[32:35], v[24:27], v[130:133]
	v_mfma_f32_16x16x32_bf16 v[134:137], v[40:43], v[24:27], v[134:137]
	v_mfma_f32_16x16x32_bf16 v[138:141], v[48:51], v[24:27], v[138:141]
	v_mfma_f32_16x16x32_bf16 v[142:145], v[56:59], v[24:27], v[142:145]
	v_mfma_f32_16x16x32_bf16 v[114:117], v[36:39], v[20:23], v[114:117]
	v_mfma_f32_16x16x32_bf16 v[118:121], v[44:47], v[20:23], v[118:121]
	v_mfma_f32_16x16x32_bf16 v[122:125], v[52:55], v[20:23], v[122:125]
	v_mfma_f32_16x16x32_bf16 v[126:129], v[60:63], v[20:23], v[126:129]
	v_mfma_f32_16x16x32_bf16 v[130:133], v[36:39], v[28:31], v[130:133]
	v_mfma_f32_16x16x32_bf16 v[134:137], v[44:47], v[28:31], v[134:137]
	v_mfma_f32_16x16x32_bf16 v[138:141], v[52:55], v[28:31], v[138:141]
	v_mfma_f32_16x16x32_bf16 v[142:145], v[60:63], v[28:31], v[142:145]
	s_nop 7
	s_nop 3
	v_add_f32_e32 v16, v114, v115
	v_add_f32_e32 v17, v116, v117
	v_add_f32_e32 v18, v118, v119
	v_add_f32_e32 v19, v120, v121
	v_add_f32_e32 v20, v122, v123
	v_add_f32_e32 v21, v124, v125
	v_add_f32_e32 v22, v126, v127
	v_add_f32_e32 v23, v128, v129
	v_add_f32_e32 v24, v16, v17
	v_add_f32_e32 v25, v18, v19
	v_add_f32_e32 v26, v20, v21
	v_add_f32_e32 v27, v22, v23
	v_add_f32_e32 v28, v24, v25
	v_add_f32_e32 v29, v26, v27
	v_add_f32_e32 v148, v28, v29
	ds_bpermute_b32 v149, v15, v148
	s_waitcnt lgkmcnt(0)
	v_add_f32_e32 v148, v148, v149
	ds_bpermute_b32 v149, v146, v148
	s_waitcnt lgkmcnt(0)
	v_add_f32_e32 v148, v148, v149
	v_mul_f32_e32 v148, s19, v148
	v_sub_f32_e32 v114, v114, v148
	v_sub_f32_e32 v115, v115, v148
	v_sub_f32_e32 v116, v116, v148
	v_sub_f32_e32 v117, v117, v148
	v_sub_f32_e32 v118, v118, v148
	v_sub_f32_e32 v119, v119, v148
	v_sub_f32_e32 v120, v120, v148
	v_sub_f32_e32 v121, v121, v148
	v_sub_f32_e32 v122, v122, v148
	v_sub_f32_e32 v123, v123, v148
	v_sub_f32_e32 v124, v124, v148
	v_sub_f32_e32 v125, v125, v148
	v_sub_f32_e32 v126, v126, v148
	v_sub_f32_e32 v127, v127, v148
	v_sub_f32_e32 v128, v128, v148
	v_sub_f32_e32 v129, v129, v148
	v_mul_f32_e32 v148, v114, v114
	v_mul_f32_e32 v149, v115, v115
	v_fmac_f32_e32 v148, v116, v116
	v_fmac_f32_e32 v149, v117, v117
	v_fmac_f32_e32 v148, v118, v118
	v_fmac_f32_e32 v149, v119, v119
	v_fmac_f32_e32 v148, v120, v120
	v_fmac_f32_e32 v149, v121, v121
	v_fmac_f32_e32 v148, v122, v122
	v_fmac_f32_e32 v149, v123, v123
	v_fmac_f32_e32 v148, v124, v124
	v_fmac_f32_e32 v149, v125, v125
	v_fmac_f32_e32 v148, v126, v126
	v_fmac_f32_e32 v149, v127, v127
	v_fmac_f32_e32 v148, v128, v128
	v_fmac_f32_e32 v149, v129, v129
	v_add_f32_e32 v148, v148, v149
	ds_bpermute_b32 v149, v15, v148
	s_waitcnt lgkmcnt(0)
	v_add_f32_e32 v148, v148, v149
	ds_bpermute_b32 v149, v146, v148
	s_waitcnt lgkmcnt(0)
	v_add_f32_e32 v148, v148, v149
	v_fmamk_f32 v148, v148, 0x3c800000, v147
	v_rsq_f32_e32 v148, v148
	s_nop 0
	v_mul_f32_e32 v114, v114, v148
	v_mul_f32_e32 v115, v115, v148
	v_mul_f32_e32 v116, v116, v148
	v_mul_f32_e32 v117, v117, v148
	v_mul_f32_e32 v118, v118, v148
	v_mul_f32_e32 v119, v119, v148
	v_mul_f32_e32 v120, v120, v148
	v_mul_f32_e32 v121, v121, v148
	v_mul_f32_e32 v122, v122, v148
	v_mul_f32_e32 v123, v123, v148
	v_mul_f32_e32 v124, v124, v148
	v_mul_f32_e32 v125, v125, v148
	v_mul_f32_e32 v126, v126, v148
	v_mul_f32_e32 v127, v127, v148
	v_mul_f32_e32 v128, v128, v148
	v_mul_f32_e32 v129, v129, v148
	v_add_f32_e32 v16, v130, v131
	v_add_f32_e32 v17, v132, v133
	v_add_f32_e32 v18, v134, v135
	v_add_f32_e32 v19, v136, v137
	v_add_f32_e32 v20, v138, v139
	v_add_f32_e32 v21, v140, v141
	v_add_f32_e32 v22, v142, v143
	v_add_f32_e32 v23, v144, v145
	v_add_f32_e32 v24, v16, v17
	v_add_f32_e32 v25, v18, v19
	v_add_f32_e32 v26, v20, v21
	v_add_f32_e32 v27, v22, v23
	v_add_f32_e32 v28, v24, v25
	v_add_f32_e32 v29, v26, v27
	v_add_f32_e32 v148, v28, v29
	ds_bpermute_b32 v149, v15, v148
	s_waitcnt lgkmcnt(0)
	v_add_f32_e32 v148, v148, v149
	ds_bpermute_b32 v149, v146, v148
	s_waitcnt lgkmcnt(0)
; #define LAS __attribute__((address_space(3)))
; __device__ __forceinline__ float bf2f(bf16_t b) { return __uint_as_float((unsigned)b << 16); }
; __device__ __forceinline__ bf16_t f2bf(float f) { return (bf16_t)(pk2(f, 0.f) & 0xffffu); }
; __device__ __forceinline__ float silu_acc(float x) { return x * frcp(1.0f + fexp(-x)); }
; #define LBAR() do { asm volatile("s_waitcnt lgkmcnt(0)" ::: "memory"); __builtin_amdgcn_s_barrier(); asm volatile("" ::: "memory"); } while (0)
; __device__ __forceinline__ void mixer_out_phase(const Ctx& X, LAS unsigned char* lds, int layer, int tid, int wave, int lane) {
;     ...
;                 const float rs = rsqrtf(s2 * (1.f / 64.f) + (mixer == 0 ? 1e-5f : 1e-6f));
;                 const int ii = 16 * (2 * half + rt) + 4 * q + j;
; #pragma unroll
;                 for (int ct = 0; ct < 4; ++ct) { LAS bf16_t* gp = GT + ii * GP + h * 64 + 16 * ct + r;
;                     const float y = d[ct] * rs * wv[ct] * silu_acc(bf2f(*gp));
;                     *gp = on ? f2bf(y) : (bf16_t)0; }
;             }
;         }
;         LBAR();
; #pragma unroll
;         for (int n = 0; n < 4; ++n) { const int idx = tid + 512 * n; __builtin_nontemporal_store(*(const LAS u32x4*)(GT + (idx >> 5) * GP + (idx & 31) * 8), (u32x4*)(mix + (row0 + (idx >> 5)) * D + moff + (idx & 31) * 8)); }
	v_add_f32_e32 v148, v148, v149
	v_mul_f32_e32 v148, s19, v148
	v_sub_f32_e32 v130, v130, v148
	v_sub_f32_e32 v131, v131, v148
	v_sub_f32_e32 v132, v132, v148
	v_sub_f32_e32 v133, v133, v148
	v_sub_f32_e32 v134, v134, v148
	v_sub_f32_e32 v135, v135, v148
	v_sub_f32_e32 v136, v136, v148
	v_sub_f32_e32 v137, v137, v148
	v_sub_f32_e32 v138, v138, v148
	v_sub_f32_e32 v139, v139, v148
	v_sub_f32_e32 v140, v140, v148
	v_sub_f32_e32 v141, v141, v148
	v_sub_f32_e32 v142, v142, v148
	v_sub_f32_e32 v143, v143, v148
	v_sub_f32_e32 v144, v144, v148
	v_sub_f32_e32 v145, v145, v148
	v_mul_f32_e32 v148, v130, v130
	v_mul_f32_e32 v149, v131, v131
	v_fmac_f32_e32 v148, v132, v132
	v_fmac_f32_e32 v149, v133, v133
	v_fmac_f32_e32 v148, v134, v134
	v_fmac_f32_e32 v149, v135, v135
	v_fmac_f32_e32 v148, v136, v136
	v_fmac_f32_e32 v149, v137, v137
	v_fmac_f32_e32 v148, v138, v138
	v_fmac_f32_e32 v149, v139, v139
	v_fmac_f32_e32 v148, v140, v140
	v_fmac_f32_e32 v149, v141, v141
	v_fmac_f32_e32 v148, v142, v142
	v_fmac_f32_e32 v149, v143, v143
	v_fmac_f32_e32 v148, v144, v144
	v_fmac_f32_e32 v149, v145, v145
	v_add_f32_e32 v148, v148, v149
	ds_bpermute_b32 v149, v15, v148
	s_waitcnt lgkmcnt(0)
	v_add_f32_e32 v148, v148, v149
	ds_bpermute_b32 v149, v146, v148
	s_waitcnt lgkmcnt(0)
	v_add_f32_e32 v148, v148, v149
	v_fmamk_f32 v148, v148, 0x3c800000, v147
	v_rsq_f32_e32 v148, v148
	s_nop 0
	v_mul_f32_e32 v130, v130, v148
	v_mul_f32_e32 v131, v131, v148
	v_mul_f32_e32 v132, v132, v148
	v_mul_f32_e32 v133, v133, v148
	v_mul_f32_e32 v134, v134, v148
	v_mul_f32_e32 v135, v135, v148
	v_mul_f32_e32 v136, v136, v148
	v_mul_f32_e32 v137, v137, v148
	v_mul_f32_e32 v138, v138, v148
	v_mul_f32_e32 v139, v139, v148
	v_mul_f32_e32 v140, v140, v148
	v_mul_f32_e32 v141, v141, v148
	v_mul_f32_e32 v142, v142, v148
	v_mul_f32_e32 v143, v143, v148
	v_mul_f32_e32 v144, v144, v148
	v_mul_f32_e32 v145, v145, v148
	s_waitcnt vmcnt(0)
	v_lshlrev_b32_e32 v150, 16, v80
	v_and_b32_e32 v151, 0xffff0000, v80
	v_lshlrev_b32_e32 v152, 16, v81
	v_and_b32_e32 v153, 0xffff0000, v81
	v_mul_f32_e32 v16, 0xbfb8aa3b, v150
	v_mul_f32_e32 v17, 0xbfb8aa3b, v151
	v_mul_f32_e32 v18, 0xbfb8aa3b, v152
	v_mul_f32_e32 v19, 0xbfb8aa3b, v153
	v_exp_f32_e32 v16, v16
	v_exp_f32_e32 v17, v17
	v_exp_f32_e32 v18, v18
	v_exp_f32_e32 v19, v19
	v_mul_f32_e32 v114, v114, v96
	v_mul_f32_e32 v115, v115, v97
	v_mul_f32_e32 v116, v116, v98
	v_mul_f32_e32 v117, v117, v99
	v_add_f32_e32 v16, 1.0, v16
	v_add_f32_e32 v17, 1.0, v17
	v_add_f32_e32 v18, 1.0, v18
	v_add_f32_e32 v19, 1.0, v19
	v_rcp_f32_e32 v16, v16
	v_rcp_f32_e32 v17, v17
	v_rcp_f32_e32 v18, v18
	v_rcp_f32_e32 v19, v19
	s_nop 0
	v_mul_f32_e32 v150, v150, v16
	v_mul_f32_e32 v151, v151, v17
	v_mul_f32_e32 v152, v152, v18
	v_mul_f32_e32 v153, v153, v19
	v_mul_f32_e32 v114, v114, v150
	v_mul_f32_e32 v115, v115, v151
	v_mul_f32_e32 v116, v116, v152
	v_mul_f32_e32 v117, v117, v153
	v_cvt_pk_bf16_f32 v80, v114, v115
	v_cvt_pk_bf16_f32 v81, v116, v117
	global_store_dwordx2 v13, v[80:81], s[44:45] nt
	v_lshlrev_b32_e32 v150, 16, v82
	v_and_b32_e32 v151, 0xffff0000, v82
	v_lshlrev_b32_e32 v152, 16, v83
	v_and_b32_e32 v153, 0xffff0000, v83
	v_mul_f32_e32 v16, 0xbfb8aa3b, v150
	v_mul_f32_e32 v17, 0xbfb8aa3b, v151
	v_mul_f32_e32 v18, 0xbfb8aa3b, v152
	v_mul_f32_e32 v19, 0xbfb8aa3b, v153
	v_exp_f32_e32 v16, v16
	v_exp_f32_e32 v17, v17
	v_exp_f32_e32 v18, v18
	v_exp_f32_e32 v19, v19
	v_mul_f32_e32 v118, v118, v100
	v_mul_f32_e32 v119, v119, v101
	v_mul_f32_e32 v120, v120, v102
	v_mul_f32_e32 v121, v121, v103
	v_add_f32_e32 v16, 1.0, v16
	v_add_f32_e32 v17, 1.0, v17
	v_add_f32_e32 v18, 1.0, v18
	v_add_f32_e32 v19, 1.0, v19
	v_rcp_f32_e32 v16, v16
	v_rcp_f32_e32 v17, v17
	v_rcp_f32_e32 v18, v18
	v_rcp_f32_e32 v19, v19
	s_nop 0
	v_mul_f32_e32 v150, v150, v16
	v_mul_f32_e32 v151, v151, v17
	v_mul_f32_e32 v152, v152, v18
	v_mul_f32_e32 v153, v153, v19
	v_mul_f32_e32 v118, v118, v150
	v_mul_f32_e32 v119, v119, v151
	v_mul_f32_e32 v120, v120, v152
	v_mul_f32_e32 v121, v121, v153
	v_cvt_pk_bf16_f32 v82, v118, v119
	v_cvt_pk_bf16_f32 v83, v120, v121
	global_store_dwordx2 v13, v[82:83], s[44:45] offset:32 nt
	v_lshlrev_b32_e32 v150, 16, v84
	v_and_b32_e32 v151, 0xffff0000, v84
	v_lshlrev_b32_e32 v152, 16, v85
	v_and_b32_e32 v153, 0xffff0000, v85
	v_mul_f32_e32 v16, 0xbfb8aa3b, v150
	v_mul_f32_e32 v17, 0xbfb8aa3b, v151
	v_mul_f32_e32 v18, 0xbfb8aa3b, v152
	v_mul_f32_e32 v19, 0xbfb8aa3b, v153
	v_exp_f32_e32 v16, v16
	v_exp_f32_e32 v17, v17
	v_exp_f32_e32 v18, v18
	v_exp_f32_e32 v19, v19
	v_mul_f32_e32 v122, v122, v104
	v_mul_f32_e32 v123, v123, v105
	v_mul_f32_e32 v124, v124, v106
	v_mul_f32_e32 v125, v125, v107
	v_add_f32_e32 v16, 1.0, v16
	v_add_f32_e32 v17, 1.0, v17
	v_add_f32_e32 v18, 1.0, v18
	v_add_f32_e32 v19, 1.0, v19
	v_rcp_f32_e32 v16, v16
	v_rcp_f32_e32 v17, v17
	v_rcp_f32_e32 v18, v18
	v_rcp_f32_e32 v19, v19
	s_nop 0
	v_mul_f32_e32 v150, v150, v16
	v_mul_f32_e32 v151, v151, v17
	v_mul_f32_e32 v152, v152, v18
	v_mul_f32_e32 v153, v153, v19
	v_mul_f32_e32 v122, v122, v150
	v_mul_f32_e32 v123, v123, v151
	v_mul_f32_e32 v124, v124, v152
	v_mul_f32_e32 v125, v125, v153
	v_cvt_pk_bf16_f32 v84, v122, v123
	v_cvt_pk_bf16_f32 v85, v124, v125
	global_store_dwordx2 v13, v[84:85], s[44:45] offset:64 nt
	v_lshlrev_b32_e32 v150, 16, v86
	v_and_b32_e32 v151, 0xffff0000, v86
	v_lshlrev_b32_e32 v152, 16, v87
	v_and_b32_e32 v153, 0xffff0000, v87
	v_mul_f32_e32 v16, 0xbfb8aa3b, v150
	v_mul_f32_e32 v17, 0xbfb8aa3b, v151
	v_mul_f32_e32 v18, 0xbfb8aa3b, v152
	v_mul_f32_e32 v19, 0xbfb8aa3b, v153
	v_exp_f32_e32 v16, v16
	v_exp_f32_e32 v17, v17
	v_exp_f32_e32 v18, v18
	v_exp_f32_e32 v19, v19
; #define LAS __attribute__((address_space(3)))
; __device__ __forceinline__ float bf2f(bf16_t b) { return __uint_as_float((unsigned)b << 16); }
; __device__ __forceinline__ bf16_t f2bf(float f) { return (bf16_t)(pk2(f, 0.f) & 0xffffu); }
; __device__ __forceinline__ float silu_acc(float x) { return x * frcp(1.0f + fexp(-x)); }
; #define LBAR() do { asm volatile("s_waitcnt lgkmcnt(0)" ::: "memory"); __builtin_amdgcn_s_barrier(); asm volatile("" ::: "memory"); } while (0)
; __device__ __forceinline__ void mixer_out_phase(const Ctx& X, LAS unsigned char* lds, int layer, int tid, int wave, int lane) {
;     ...
;                 for (int ct = 0; ct < 4; ++ct) { LAS bf16_t* gp = GT + ii * GP + h * 64 + 16 * ct + r;
;                     const float y = d[ct] * rs * wv[ct] * silu_acc(bf2f(*gp));
;                     *gp = on ? f2bf(y) : (bf16_t)0; }
;             }
;         }
;         LBAR();
; #pragma unroll
;         for (int n = 0; n < 4; ++n) { const int idx = tid + 512 * n; __builtin_nontemporal_store(*(const LAS u32x4*)(GT + (idx >> 5) * GP + (idx & 31) * 8), (u32x4*)(mix + (row0 + (idx >> 5)) * D + moff + (idx & 31) * 8)); }
;         LBAR();
	v_mul_f32_e32 v126, v126, v108
	v_mul_f32_e32 v127, v127, v109
	v_mul_f32_e32 v128, v128, v110
	v_mul_f32_e32 v129, v129, v111
	v_add_f32_e32 v16, 1.0, v16
	v_add_f32_e32 v17, 1.0, v17
	v_add_f32_e32 v18, 1.0, v18
	v_add_f32_e32 v19, 1.0, v19
	v_rcp_f32_e32 v16, v16
	v_rcp_f32_e32 v17, v17
	v_rcp_f32_e32 v18, v18
	v_rcp_f32_e32 v19, v19
	s_nop 0
	v_mul_f32_e32 v150, v150, v16
	v_mul_f32_e32 v151, v151, v17
	v_mul_f32_e32 v152, v152, v18
	v_mul_f32_e32 v153, v153, v19
	v_mul_f32_e32 v126, v126, v150
	v_mul_f32_e32 v127, v127, v151
	v_mul_f32_e32 v128, v128, v152
	v_mul_f32_e32 v129, v129, v153
	v_cvt_pk_bf16_f32 v86, v126, v127
	v_cvt_pk_bf16_f32 v87, v128, v129
	global_store_dwordx2 v13, v[86:87], s[44:45] offset:96 nt
	v_lshlrev_b32_e32 v150, 16, v88
	v_and_b32_e32 v151, 0xffff0000, v88
	v_lshlrev_b32_e32 v152, 16, v89
	v_and_b32_e32 v153, 0xffff0000, v89
	v_mul_f32_e32 v16, 0xbfb8aa3b, v150
	v_mul_f32_e32 v17, 0xbfb8aa3b, v151
	v_mul_f32_e32 v18, 0xbfb8aa3b, v152
	v_mul_f32_e32 v19, 0xbfb8aa3b, v153
	v_exp_f32_e32 v16, v16
	v_exp_f32_e32 v17, v17
	v_exp_f32_e32 v18, v18
	v_exp_f32_e32 v19, v19
	v_mul_f32_e32 v130, v130, v96
	v_mul_f32_e32 v131, v131, v97
	v_mul_f32_e32 v132, v132, v98
	v_mul_f32_e32 v133, v133, v99
	v_add_f32_e32 v16, 1.0, v16
	v_add_f32_e32 v17, 1.0, v17
	v_add_f32_e32 v18, 1.0, v18
	v_add_f32_e32 v19, 1.0, v19
	v_rcp_f32_e32 v16, v16
	v_rcp_f32_e32 v17, v17
	v_rcp_f32_e32 v18, v18
	v_rcp_f32_e32 v19, v19
	s_nop 0
	v_mul_f32_e32 v150, v150, v16
	v_mul_f32_e32 v151, v151, v17
	v_mul_f32_e32 v152, v152, v18
	v_mul_f32_e32 v153, v153, v19
	v_mul_f32_e32 v130, v130, v150
	v_mul_f32_e32 v131, v131, v151
	v_mul_f32_e32 v132, v132, v152
	v_mul_f32_e32 v133, v133, v153
	v_cvt_pk_bf16_f32 v88, v130, v131
	v_cvt_pk_bf16_f32 v89, v132, v133
	global_store_dwordx2 v13, v[88:89], s[46:47] nt
	v_lshlrev_b32_e32 v150, 16, v90
	v_and_b32_e32 v151, 0xffff0000, v90
	v_lshlrev_b32_e32 v152, 16, v91
	v_and_b32_e32 v153, 0xffff0000, v91
	v_mul_f32_e32 v16, 0xbfb8aa3b, v150
	v_mul_f32_e32 v17, 0xbfb8aa3b, v151
	v_mul_f32_e32 v18, 0xbfb8aa3b, v152
	v_mul_f32_e32 v19, 0xbfb8aa3b, v153
	v_exp_f32_e32 v16, v16
	v_exp_f32_e32 v17, v17
	v_exp_f32_e32 v18, v18
	v_exp_f32_e32 v19, v19
	v_mul_f32_e32 v134, v134, v100
	v_mul_f32_e32 v135, v135, v101
	v_mul_f32_e32 v136, v136, v102
	v_mul_f32_e32 v137, v137, v103
	v_add_f32_e32 v16, 1.0, v16
	v_add_f32_e32 v17, 1.0, v17
	v_add_f32_e32 v18, 1.0, v18
	v_add_f32_e32 v19, 1.0, v19
	v_rcp_f32_e32 v16, v16
	v_rcp_f32_e32 v17, v17
	v_rcp_f32_e32 v18, v18
	v_rcp_f32_e32 v19, v19
	s_nop 0
	v_mul_f32_e32 v150, v150, v16
	v_mul_f32_e32 v151, v151, v17
	v_mul_f32_e32 v152, v152, v18
	v_mul_f32_e32 v153, v153, v19
	v_mul_f32_e32 v134, v134, v150
	v_mul_f32_e32 v135, v135, v151
	v_mul_f32_e32 v136, v136, v152
	v_mul_f32_e32 v137, v137, v153
	v_cvt_pk_bf16_f32 v90, v134, v135
	v_cvt_pk_bf16_f32 v91, v136, v137
	global_store_dwordx2 v13, v[90:91], s[46:47] offset:32 nt
	v_lshlrev_b32_e32 v150, 16, v92
	v_and_b32_e32 v151, 0xffff0000, v92
	v_lshlrev_b32_e32 v152, 16, v93
	v_and_b32_e32 v153, 0xffff0000, v93
	v_mul_f32_e32 v16, 0xbfb8aa3b, v150
	v_mul_f32_e32 v17, 0xbfb8aa3b, v151
	v_mul_f32_e32 v18, 0xbfb8aa3b, v152
	v_mul_f32_e32 v19, 0xbfb8aa3b, v153
	v_exp_f32_e32 v16, v16
	v_exp_f32_e32 v17, v17
	v_exp_f32_e32 v18, v18
	v_exp_f32_e32 v19, v19
	v_mul_f32_e32 v138, v138, v104
	v_mul_f32_e32 v139, v139, v105
	v_mul_f32_e32 v140, v140, v106
	v_mul_f32_e32 v141, v141, v107
	v_add_f32_e32 v16, 1.0, v16
	v_add_f32_e32 v17, 1.0, v17
	v_add_f32_e32 v18, 1.0, v18
	v_add_f32_e32 v19, 1.0, v19
	v_rcp_f32_e32 v16, v16
	v_rcp_f32_e32 v17, v17
	v_rcp_f32_e32 v18, v18
	v_rcp_f32_e32 v19, v19
	s_nop 0
	v_mul_f32_e32 v150, v150, v16
	v_mul_f32_e32 v151, v151, v17
	v_mul_f32_e32 v152, v152, v18
	v_mul_f32_e32 v153, v153, v19
	v_mul_f32_e32 v138, v138, v150
	v_mul_f32_e32 v139, v139, v151
	v_mul_f32_e32 v140, v140, v152
	v_mul_f32_e32 v141, v141, v153
	v_cvt_pk_bf16_f32 v92, v138, v139
	v_cvt_pk_bf16_f32 v93, v140, v141
	global_store_dwordx2 v13, v[92:93], s[46:47] offset:64 nt
	v_lshlrev_b32_e32 v150, 16, v94
	v_and_b32_e32 v151, 0xffff0000, v94
	v_lshlrev_b32_e32 v152, 16, v95
	v_and_b32_e32 v153, 0xffff0000, v95
	v_mul_f32_e32 v16, 0xbfb8aa3b, v150
	v_mul_f32_e32 v17, 0xbfb8aa3b, v151
	v_mul_f32_e32 v18, 0xbfb8aa3b, v152
	v_mul_f32_e32 v19, 0xbfb8aa3b, v153
	v_exp_f32_e32 v16, v16
	v_exp_f32_e32 v17, v17
	v_exp_f32_e32 v18, v18
	v_exp_f32_e32 v19, v19
	v_mul_f32_e32 v142, v142, v108
	v_mul_f32_e32 v143, v143, v109
	v_mul_f32_e32 v144, v144, v110
	v_mul_f32_e32 v145, v145, v111
	v_add_f32_e32 v16, 1.0, v16
	v_add_f32_e32 v17, 1.0, v17
	v_add_f32_e32 v18, 1.0, v18
	v_add_f32_e32 v19, 1.0, v19
	v_rcp_f32_e32 v16, v16
	v_rcp_f32_e32 v17, v17
	v_rcp_f32_e32 v18, v18
	v_rcp_f32_e32 v19, v19
	s_nop 0
	v_mul_f32_e32 v150, v150, v16
	v_mul_f32_e32 v151, v151, v17
	v_mul_f32_e32 v152, v152, v18
	v_mul_f32_e32 v153, v153, v19
	v_mul_f32_e32 v142, v142, v150
	v_mul_f32_e32 v143, v143, v151
	v_mul_f32_e32 v144, v144, v152
	v_mul_f32_e32 v145, v145, v153
	v_cvt_pk_bf16_f32 v94, v142, v143
	v_cvt_pk_bf16_f32 v95, v144, v145
	global_store_dwordx2 v13, v[94:95], s[46:47] offset:96 nt
	s_add_i32 s10, s10, s18
	s_cmpk_lt_i32 s10, 0x600
	s_cbranch_scc1 .Lmo_loop
	v_readlane_b32 s54, v255, 7
	v_readlane_b32 s56, v255, 9
	v_readlane_b32 s58, v255, 11
	v_readlane_b32 s48, v255, 13
	v_readlane_b32 s50, v255, 15
	v_readlane_b32 s52, v255, 17
	v_readlane_b32 s55, v255, 8
	v_readlane_b32 s57, v255, 10
	v_readlane_b32 s59, v255, 12
	v_readlane_b32 s49, v255, 14
	v_readlane_b32 s51, v255, 16
	v_readlane_b32 s53, v255, 18
	s_mov_b64 s[22:23], s[64:65]
	v_readlane_b32 s19, v255, 26
